# v8 + SP2 load segments: ds_read_b128 spread between the LDS-DMA pieces (overlap LDS and TA queues)
# speedup vs baseline: 1.0314x; 1.0001x over previous
.LBB0_121:
	ds_read_b128 v[164:167], v131
	ds_read_b128 v[168:171], v131 offset:1024
	ds_read_b128 v[172:175], v131 offset:2048
	ds_read_b128 v[176:179], v131 offset:3072
	ds_read_b128 v[180:183], v160
	ds_read_b128 v[184:187], v160 offset:1024
	ds_read_b128 v[188:191], v160 offset:2048
	ds_read_b128 v[192:195], v160 offset:3072
	s_add_i32 s55, s52, 0xfffc0080
	s_cmp_eq_u32 s54, 12
	s_cselect_b32 s57, s16, s55
	s_cselect_b32 s56, s17, s53
	s_or_b32 s55, s57, 0x80
	ds_read_b128 v[196:199], v161
	ds_read_b128 v[200:203], v161 offset:1024
	ds_read_b128 v[204:207], v161 offset:2048
	ds_read_b128 v[208:211], v161 offset:3072
	ds_read_b128 v[212:215], v161 offset:4096
	ds_read_b128 v[216:219], v161 offset:5120
	ds_read_b128 v[220:223], v161 offset:6144
	ds_read_b128 v[224:227], v161 offset:7168
	s_mov_b32 m0, s40
	s_nop 0
	buffer_load_dwordx4 v156, s[12:15], s52 offen lds
	s_nop 0
	s_mov_b32 m0, s41
	s_nop 0
	buffer_load_dwordx4 v157, s[12:15], s52 offen lds
	s_waitcnt vmcnt(8)
	s_waitcnt lgkmcnt(0)
	s_barrier
	s_setprio 1
	s_waitcnt lgkmcnt(7)
	v_mfma_f32_16x16x32_bf16 v[126:129], v[164:167], v[196:199], v[126:129]
	v_mfma_f32_16x16x32_bf16 v[122:125], v[172:175], v[196:199], v[122:125]
	s_waitcnt lgkmcnt(5)
	v_mfma_f32_16x16x32_bf16 v[118:121], v[164:167], v[204:207], v[118:121]
	v_mfma_f32_16x16x32_bf16 v[110:113], v[172:175], v[204:207], v[110:113]
	s_waitcnt lgkmcnt(3)
	v_mfma_f32_16x16x32_bf16 v[102:105], v[164:167], v[212:215], v[102:105]
	v_mfma_f32_16x16x32_bf16 v[94:97], v[172:175], v[212:215], v[94:97]
	s_waitcnt lgkmcnt(1)
	v_mfma_f32_16x16x32_bf16 v[86:89], v[164:167], v[220:223], v[86:89]
	v_mfma_f32_16x16x32_bf16 v[78:81], v[172:175], v[220:223], v[78:81]
	v_mfma_f32_16x16x32_bf16 v[126:129], v[168:171], v[200:203], v[126:129]
	v_mfma_f32_16x16x32_bf16 v[122:125], v[176:179], v[200:203], v[122:125]
	v_mfma_f32_16x16x32_bf16 v[118:121], v[168:171], v[208:211], v[118:121]
	v_mfma_f32_16x16x32_bf16 v[110:113], v[176:179], v[208:211], v[110:113]
	v_mfma_f32_16x16x32_bf16 v[102:105], v[168:171], v[216:219], v[102:105]
	v_mfma_f32_16x16x32_bf16 v[94:97], v[176:179], v[216:219], v[94:97]
	s_waitcnt lgkmcnt(0)
	v_mfma_f32_16x16x32_bf16 v[86:89], v[168:171], v[224:227], v[86:89]
	v_mfma_f32_16x16x32_bf16 v[78:81], v[176:179], v[224:227], v[78:81]
	s_setprio 0
	s_setprio 1
	v_mfma_f32_16x16x32_bf16 v[114:117], v[180:183], v[196:199], v[114:117]
	v_mfma_f32_16x16x32_bf16 v[106:109], v[188:191], v[196:199], v[106:109]
	v_mfma_f32_16x16x32_bf16 v[98:101], v[180:183], v[204:207], v[98:101]
	v_mfma_f32_16x16x32_bf16 v[90:93], v[188:191], v[204:207], v[90:93]
	v_mfma_f32_16x16x32_bf16 v[82:85], v[180:183], v[212:215], v[82:85]
	v_mfma_f32_16x16x32_bf16 v[74:77], v[188:191], v[212:215], v[74:77]
	v_mfma_f32_16x16x32_bf16 v[70:73], v[180:183], v[220:223], v[70:73]
	v_mfma_f32_16x16x32_bf16 v[66:69], v[188:191], v[220:223], v[66:69]
	v_mfma_f32_16x16x32_bf16 v[114:117], v[184:187], v[200:203], v[114:117]
	v_mfma_f32_16x16x32_bf16 v[106:109], v[192:195], v[200:203], v[106:109]
	v_mfma_f32_16x16x32_bf16 v[98:101], v[184:187], v[208:211], v[98:101]
	v_mfma_f32_16x16x32_bf16 v[90:93], v[192:195], v[208:211], v[90:93]
	v_mfma_f32_16x16x32_bf16 v[82:85], v[184:187], v[216:219], v[82:85]
	v_mfma_f32_16x16x32_bf16 v[74:77], v[192:195], v[216:219], v[74:77]
	v_mfma_f32_16x16x32_bf16 v[70:73], v[184:187], v[224:227], v[70:73]
	v_mfma_f32_16x16x32_bf16 v[66:69], v[192:195], v[224:227], v[66:69]
	s_setprio 0
	s_barrier
	ds_read_b128 v[196:199], v161 offset:16384
	ds_read_b128 v[200:203], v161 offset:17408
	s_mov_b32 m0, s22
	s_nop 0
	buffer_load_dwordx4 v154, s[8:11], s56 offen lds
	ds_read_b128 v[204:207], v161 offset:18432
	ds_read_b128 v[208:211], v161 offset:19456
	s_add_i32 s58, s56, 0x40000
	s_mov_b32 m0, s23
	s_nop 0
	buffer_load_dwordx4 v155, s[8:11], s56 offen lds
	ds_read_b128 v[212:215], v161 offset:20480
	ds_read_b128 v[216:219], v161 offset:21504
	s_nop 0
	s_mov_b32 m0, s24
	s_nop 0
	buffer_load_dwordx4 v154, s[8:11], s58 offen lds
	ds_read_b128 v[220:223], v161 offset:22528
	ds_read_b128 v[224:227], v161 offset:23552
	s_nop 0
	s_mov_b32 m0, s25
	s_nop 0
	buffer_load_dwordx4 v155, s[8:11], s58 offen lds
	s_nop 0
	s_mov_b32 m0, s21
	s_nop 0
	buffer_load_dwordx4 v156, s[12:15], s57 offen lds
	s_nop 0
	s_mov_b32 m0, s27
	s_nop 0
	buffer_load_dwordx4 v157, s[12:15], s57 offen lds
	s_waitcnt vmcnt(8)
	s_waitcnt lgkmcnt(0)
	s_barrier
	s_setprio 1
	s_waitcnt lgkmcnt(7)
	v_mfma_f32_16x16x32_bf16 v[62:65], v[164:167], v[196:199], v[62:65]
	v_mfma_f32_16x16x32_bf16 v[58:61], v[172:175], v[196:199], v[58:61]
	s_waitcnt lgkmcnt(5)
	v_mfma_f32_16x16x32_bf16 v[54:57], v[164:167], v[204:207], v[54:57]
	v_mfma_f32_16x16x32_bf16 v[46:49], v[172:175], v[204:207], v[46:49]
	s_waitcnt lgkmcnt(3)
	v_mfma_f32_16x16x32_bf16 v[38:41], v[164:167], v[212:215], v[38:41]
	v_mfma_f32_16x16x32_bf16 v[30:33], v[172:175], v[212:215], v[30:33]
	s_waitcnt lgkmcnt(1)
	v_mfma_f32_16x16x32_bf16 v[22:25], v[164:167], v[220:223], v[22:25]
	v_mfma_f32_16x16x32_bf16 v[14:17], v[172:175], v[220:223], v[14:17]
	v_mfma_f32_16x16x32_bf16 v[62:65], v[168:171], v[200:203], v[62:65]
	v_mfma_f32_16x16x32_bf16 v[58:61], v[176:179], v[200:203], v[58:61]
	v_mfma_f32_16x16x32_bf16 v[54:57], v[168:171], v[208:211], v[54:57]
	v_mfma_f32_16x16x32_bf16 v[46:49], v[176:179], v[208:211], v[46:49]
	v_mfma_f32_16x16x32_bf16 v[38:41], v[168:171], v[216:219], v[38:41]
	v_mfma_f32_16x16x32_bf16 v[30:33], v[176:179], v[216:219], v[30:33]
	s_waitcnt lgkmcnt(0)
	v_mfma_f32_16x16x32_bf16 v[22:25], v[168:171], v[224:227], v[22:25]
	v_mfma_f32_16x16x32_bf16 v[14:17], v[176:179], v[224:227], v[14:17]
	s_setprio 0
	s_setprio 1
	v_mfma_f32_16x16x32_bf16 v[50:53], v[180:183], v[196:199], v[50:53]
	v_mfma_f32_16x16x32_bf16 v[42:45], v[188:191], v[196:199], v[42:45]
	v_mfma_f32_16x16x32_bf16 v[34:37], v[180:183], v[204:207], v[34:37]
	v_mfma_f32_16x16x32_bf16 v[26:29], v[188:191], v[204:207], v[26:29]
	v_mfma_f32_16x16x32_bf16 v[18:21], v[180:183], v[212:215], v[18:21]
	v_mfma_f32_16x16x32_bf16 v[10:13], v[188:191], v[212:215], v[10:13]
	v_mfma_f32_16x16x32_bf16 v[6:9], v[180:183], v[220:223], v[6:9]
	v_mfma_f32_16x16x32_bf16 v[2:5], v[188:191], v[220:223], v[2:5]
	v_mfma_f32_16x16x32_bf16 v[50:53], v[184:187], v[200:203], v[50:53]
	v_mfma_f32_16x16x32_bf16 v[42:45], v[192:195], v[200:203], v[42:45]
	v_mfma_f32_16x16x32_bf16 v[34:37], v[184:187], v[208:211], v[34:37]
	v_mfma_f32_16x16x32_bf16 v[26:29], v[192:195], v[208:211], v[26:29]
	v_mfma_f32_16x16x32_bf16 v[18:21], v[184:187], v[216:219], v[18:21]
	v_mfma_f32_16x16x32_bf16 v[10:13], v[192:195], v[216:219], v[10:13]
	v_mfma_f32_16x16x32_bf16 v[6:9], v[184:187], v[224:227], v[6:9]
	v_mfma_f32_16x16x32_bf16 v[2:5], v[192:195], v[224:227], v[2:5]
	s_setprio 0
	s_barrier
	ds_read_b128 v[164:167], v162
	ds_read_b128 v[168:171], v162 offset:1024
	ds_read_b128 v[172:175], v162 offset:2048
	ds_read_b128 v[176:179], v162 offset:3072
	ds_read_b128 v[180:183], v163
	ds_read_b128 v[184:187], v163 offset:1024
	ds_read_b128 v[188:191], v163 offset:2048
	ds_read_b128 v[192:195], v163 offset:3072
	ds_read_b128 v[196:199], v161 offset:32768
	ds_read_b128 v[200:203], v161 offset:33792
	ds_read_b128 v[204:207], v161 offset:34816
	ds_read_b128 v[208:211], v161 offset:35840
	ds_read_b128 v[212:215], v161 offset:36864
	ds_read_b128 v[216:219], v161 offset:37888
	ds_read_b128 v[220:223], v161 offset:38912
	ds_read_b128 v[224:227], v161 offset:39936
	s_add_i32 s57, s57, 0x40000
	s_mov_b32 m0, s28
	s_nop 0
	buffer_load_dwordx4 v156, s[12:15], s57 offen lds
	s_nop 0
	s_mov_b32 m0, s30
	s_nop 0
	buffer_load_dwordx4 v157, s[12:15], s57 offen lds
	s_waitcnt vmcnt(8)
	s_waitcnt lgkmcnt(0)
	s_barrier
	s_setprio 1
	s_waitcnt lgkmcnt(7)
	v_mfma_f32_16x16x32_bf16 v[126:129], v[164:167], v[196:199], v[126:129]
	v_mfma_f32_16x16x32_bf16 v[122:125], v[172:175], v[196:199], v[122:125]
	s_waitcnt lgkmcnt(5)
	v_mfma_f32_16x16x32_bf16 v[118:121], v[164:167], v[204:207], v[118:121]
	v_mfma_f32_16x16x32_bf16 v[110:113], v[172:175], v[204:207], v[110:113]
	s_waitcnt lgkmcnt(3)
	v_mfma_f32_16x16x32_bf16 v[102:105], v[164:167], v[212:215], v[102:105]
	v_mfma_f32_16x16x32_bf16 v[94:97], v[172:175], v[212:215], v[94:97]
	s_waitcnt lgkmcnt(1)
	v_mfma_f32_16x16x32_bf16 v[86:89], v[164:167], v[220:223], v[86:89]
	v_mfma_f32_16x16x32_bf16 v[78:81], v[172:175], v[220:223], v[78:81]
	v_mfma_f32_16x16x32_bf16 v[126:129], v[168:171], v[200:203], v[126:129]
	v_mfma_f32_16x16x32_bf16 v[122:125], v[176:179], v[200:203], v[122:125]
	v_mfma_f32_16x16x32_bf16 v[118:121], v[168:171], v[208:211], v[118:121]
	v_mfma_f32_16x16x32_bf16 v[110:113], v[176:179], v[208:211], v[110:113]
	v_mfma_f32_16x16x32_bf16 v[102:105], v[168:171], v[216:219], v[102:105]
	v_mfma_f32_16x16x32_bf16 v[94:97], v[176:179], v[216:219], v[94:97]
	s_waitcnt lgkmcnt(0)
	v_mfma_f32_16x16x32_bf16 v[86:89], v[168:171], v[224:227], v[86:89]
	v_mfma_f32_16x16x32_bf16 v[78:81], v[176:179], v[224:227], v[78:81]
	s_setprio 0
	s_setprio 1
	v_mfma_f32_16x16x32_bf16 v[114:117], v[180:183], v[196:199], v[114:117]
	v_mfma_f32_16x16x32_bf16 v[106:109], v[188:191], v[196:199], v[106:109]
	v_mfma_f32_16x16x32_bf16 v[98:101], v[180:183], v[204:207], v[98:101]
	v_mfma_f32_16x16x32_bf16 v[90:93], v[188:191], v[204:207], v[90:93]
	v_mfma_f32_16x16x32_bf16 v[82:85], v[180:183], v[212:215], v[82:85]
	v_mfma_f32_16x16x32_bf16 v[74:77], v[188:191], v[212:215], v[74:77]
	v_mfma_f32_16x16x32_bf16 v[70:73], v[180:183], v[220:223], v[70:73]
	v_mfma_f32_16x16x32_bf16 v[66:69], v[188:191], v[220:223], v[66:69]
	v_mfma_f32_16x16x32_bf16 v[114:117], v[184:187], v[200:203], v[114:117]
	v_mfma_f32_16x16x32_bf16 v[106:109], v[192:195], v[200:203], v[106:109]
	v_mfma_f32_16x16x32_bf16 v[98:101], v[184:187], v[208:211], v[98:101]
	v_mfma_f32_16x16x32_bf16 v[90:93], v[192:195], v[208:211], v[90:93]
	v_mfma_f32_16x16x32_bf16 v[82:85], v[184:187], v[216:219], v[82:85]
	v_mfma_f32_16x16x32_bf16 v[74:77], v[192:195], v[216:219], v[74:77]
	v_mfma_f32_16x16x32_bf16 v[70:73], v[184:187], v[224:227], v[70:73]
	v_mfma_f32_16x16x32_bf16 v[66:69], v[192:195], v[224:227], v[66:69]
	s_setprio 0
	s_barrier
	ds_read_b128 v[196:199], v161 offset:49152
	ds_read_b128 v[200:203], v161 offset:50176
	s_or_b32 s57, s56, 0x80
	s_mov_b32 m0, s34
	s_nop 0
	buffer_load_dwordx4 v154, s[8:11], s57 offen lds
	ds_read_b128 v[204:207], v161 offset:51200
	ds_read_b128 v[208:211], v161 offset:52224
	s_add_i32 s56, s56, 0x40080
	s_mov_b32 m0, s35
	s_nop 0
	buffer_load_dwordx4 v155, s[8:11], s57 offen lds
	ds_read_b128 v[212:215], v161 offset:53248
	ds_read_b128 v[216:219], v161 offset:54272
	s_nop 0
	s_mov_b32 m0, s38
	s_nop 0
	buffer_load_dwordx4 v154, s[8:11], s56 offen lds
	ds_read_b128 v[220:223], v161 offset:55296
	ds_read_b128 v[224:227], v161 offset:56320
	s_nop 0
	s_mov_b32 m0, s39
	s_nop 0
	buffer_load_dwordx4 v155, s[8:11], s56 offen lds
	s_nop 0
	s_mov_b32 m0, s36
	s_nop 0
	buffer_load_dwordx4 v156, s[12:15], s55 offen lds
	s_nop 0
	s_mov_b32 m0, s37
	s_nop 0
	buffer_load_dwordx4 v157, s[12:15], s55 offen lds
	s_waitcnt vmcnt(8)
	s_waitcnt lgkmcnt(0)
	s_barrier
	s_setprio 1
	s_waitcnt lgkmcnt(7)
	v_mfma_f32_16x16x32_bf16 v[62:65], v[164:167], v[196:199], v[62:65]
	v_mfma_f32_16x16x32_bf16 v[58:61], v[172:175], v[196:199], v[58:61]
	s_waitcnt lgkmcnt(5)
	v_mfma_f32_16x16x32_bf16 v[54:57], v[164:167], v[204:207], v[54:57]
	v_mfma_f32_16x16x32_bf16 v[46:49], v[172:175], v[204:207], v[46:49]
	s_waitcnt lgkmcnt(3)
	v_mfma_f32_16x16x32_bf16 v[38:41], v[164:167], v[212:215], v[38:41]
	v_mfma_f32_16x16x32_bf16 v[30:33], v[172:175], v[212:215], v[30:33]
	s_waitcnt lgkmcnt(1)
	v_mfma_f32_16x16x32_bf16 v[22:25], v[164:167], v[220:223], v[22:25]
	v_mfma_f32_16x16x32_bf16 v[14:17], v[172:175], v[220:223], v[14:17]
	v_mfma_f32_16x16x32_bf16 v[62:65], v[168:171], v[200:203], v[62:65]
	v_mfma_f32_16x16x32_bf16 v[58:61], v[176:179], v[200:203], v[58:61]
	v_mfma_f32_16x16x32_bf16 v[54:57], v[168:171], v[208:211], v[54:57]
	v_mfma_f32_16x16x32_bf16 v[46:49], v[176:179], v[208:211], v[46:49]
	v_mfma_f32_16x16x32_bf16 v[38:41], v[168:171], v[216:219], v[38:41]
	v_mfma_f32_16x16x32_bf16 v[30:33], v[176:179], v[216:219], v[30:33]
	s_waitcnt lgkmcnt(0)
	v_mfma_f32_16x16x32_bf16 v[22:25], v[168:171], v[224:227], v[22:25]
	v_mfma_f32_16x16x32_bf16 v[14:17], v[176:179], v[224:227], v[14:17]
	s_setprio 0
	s_setprio 1
	v_mfma_f32_16x16x32_bf16 v[50:53], v[180:183], v[196:199], v[50:53]
	v_mfma_f32_16x16x32_bf16 v[42:45], v[188:191], v[196:199], v[42:45]
	v_mfma_f32_16x16x32_bf16 v[34:37], v[180:183], v[204:207], v[34:37]
	v_mfma_f32_16x16x32_bf16 v[26:29], v[188:191], v[204:207], v[26:29]
	v_mfma_f32_16x16x32_bf16 v[18:21], v[180:183], v[212:215], v[18:21]
	v_mfma_f32_16x16x32_bf16 v[10:13], v[188:191], v[212:215], v[10:13]
	v_mfma_f32_16x16x32_bf16 v[6:9], v[180:183], v[220:223], v[6:9]
	v_mfma_f32_16x16x32_bf16 v[2:5], v[188:191], v[220:223], v[2:5]
	v_mfma_f32_16x16x32_bf16 v[50:53], v[184:187], v[200:203], v[50:53]
	v_mfma_f32_16x16x32_bf16 v[42:45], v[192:195], v[200:203], v[42:45]
	v_mfma_f32_16x16x32_bf16 v[34:37], v[184:187], v[208:211], v[34:37]
	v_mfma_f32_16x16x32_bf16 v[26:29], v[192:195], v[208:211], v[26:29]
	v_mfma_f32_16x16x32_bf16 v[18:21], v[184:187], v[216:219], v[18:21]
	v_mfma_f32_16x16x32_bf16 v[10:13], v[192:195], v[216:219], v[10:13]
	v_mfma_f32_16x16x32_bf16 v[6:9], v[184:187], v[224:227], v[6:9]
	v_mfma_f32_16x16x32_bf16 v[2:5], v[192:195], v[224:227], v[2:5]
	s_setprio 0
	s_barrier
	s_add_i32 s54, s54, 2
	s_addk_i32 s52, 0x100
	s_addk_i32 s53, 0x100
	s_cmp_gt_u32 s54, 13
	s_cbranch_scc0 .LBB0_121
	s_and_b64 vcc, exec, s[6:7]
	s_cbranch_vccz .LBB0_126
	s_barrier
	s_cmp_gt_i32 s46, 3
	s_mov_b64 s[16:17], -1
	s_cbranch_scc1 .LBB0_127

.LBB0_223:
	v_add_u32_e32 v150, 0x10000, v132
	v_add_u32_e32 v166, 0x14000, v132
	ds_read_b128 v[134:137], v150
	ds_read_b128 v[142:145], v150 offset:1024
	ds_read_b128 v[146:149], v150 offset:2048
	ds_read_b128 v[150:153], v150 offset:3072
	ds_read_b128 v[154:157], v166
	ds_read_b128 v[158:161], v166 offset:1024
	ds_read_b128 v[162:165], v166 offset:2048
	ds_read_b128 v[166:169], v166 offset:3072
	s_add_i32 s63, s39, s60
	s_add_i32 s62, s34, s60
	s_add_i32 s61, s63, 0x800
	s_addk_i32 s62, 0x800
	s_cmp_eq_u32 s60, 0
	s_cselect_b32 s64, s55, s61
	s_cselect_b32 s62, s58, s62
	s_or_b32 s61, s64, 0x80
	ds_read_b128 v[170:173], v133
	ds_read_b128 v[174:177], v133 offset:1024
	ds_read_b128 v[178:181], v133 offset:2048
	ds_read_b128 v[182:185], v133 offset:3072
	ds_read_b128 v[186:189], v133 offset:4096
	ds_read_b128 v[190:193], v133 offset:5120
	ds_read_b128 v[194:197], v133 offset:6144
	ds_read_b128 v[198:201], v133 offset:7168
	s_add_i32 s63, s63, 0x40780
	s_mov_b32 m0, s49
	s_nop 0
	buffer_load_dwordx4 v130, s[12:15], s63 offen lds
	s_nop 0
	s_mov_b32 m0, s50
	s_nop 0
	buffer_load_dwordx4 v131, s[12:15], s63 offen lds
	s_waitcnt vmcnt(8)
	s_waitcnt lgkmcnt(0)
	s_barrier
	s_setprio 1
	s_waitcnt lgkmcnt(7)
	v_mfma_f32_16x16x32_bf16 v[138:141], v[134:137], v[170:173], v[138:141]
	v_mfma_f32_16x16x32_bf16 v[126:129], v[146:149], v[170:173], v[126:129]
	s_waitcnt lgkmcnt(5)
	v_mfma_f32_16x16x32_bf16 v[110:113], v[134:137], v[178:181], v[110:113]
	v_mfma_f32_16x16x32_bf16 v[106:109], v[146:149], v[178:181], v[106:109]
	s_waitcnt lgkmcnt(3)
	v_mfma_f32_16x16x32_bf16 v[94:97], v[134:137], v[186:189], v[94:97]
	v_mfma_f32_16x16x32_bf16 v[90:93], v[146:149], v[186:189], v[90:93]
	s_waitcnt lgkmcnt(1)
	v_mfma_f32_16x16x32_bf16 v[78:81], v[134:137], v[194:197], v[78:81]
	v_mfma_f32_16x16x32_bf16 v[74:77], v[146:149], v[194:197], v[74:77]
	v_mfma_f32_16x16x32_bf16 v[138:141], v[142:145], v[174:177], v[138:141]
	v_mfma_f32_16x16x32_bf16 v[126:129], v[150:153], v[174:177], v[126:129]
	v_mfma_f32_16x16x32_bf16 v[110:113], v[142:145], v[182:185], v[110:113]
	v_mfma_f32_16x16x32_bf16 v[106:109], v[150:153], v[182:185], v[106:109]
	v_mfma_f32_16x16x32_bf16 v[94:97], v[142:145], v[190:193], v[94:97]
	v_mfma_f32_16x16x32_bf16 v[90:93], v[150:153], v[190:193], v[90:93]
	s_waitcnt lgkmcnt(0)
	v_mfma_f32_16x16x32_bf16 v[78:81], v[142:145], v[198:201], v[78:81]
	v_mfma_f32_16x16x32_bf16 v[74:77], v[150:153], v[198:201], v[74:77]
	s_setprio 0
	s_setprio 1
	v_mfma_f32_16x16x32_bf16 v[118:121], v[154:157], v[170:173], v[118:121]
	v_mfma_f32_16x16x32_bf16 v[114:117], v[162:165], v[170:173], v[114:117]
	v_mfma_f32_16x16x32_bf16 v[102:105], v[154:157], v[178:181], v[102:105]
	v_mfma_f32_16x16x32_bf16 v[98:101], v[162:165], v[178:181], v[98:101]
	v_mfma_f32_16x16x32_bf16 v[86:89], v[154:157], v[186:189], v[86:89]
	v_mfma_f32_16x16x32_bf16 v[82:85], v[162:165], v[186:189], v[82:85]
	v_mfma_f32_16x16x32_bf16 v[70:73], v[154:157], v[194:197], v[70:73]
	v_mfma_f32_16x16x32_bf16 v[66:69], v[162:165], v[194:197], v[66:69]
	v_mfma_f32_16x16x32_bf16 v[118:121], v[158:161], v[174:177], v[118:121]
	v_mfma_f32_16x16x32_bf16 v[114:117], v[166:169], v[174:177], v[114:117]
	v_mfma_f32_16x16x32_bf16 v[102:105], v[158:161], v[182:185], v[102:105]
	v_mfma_f32_16x16x32_bf16 v[98:101], v[166:169], v[182:185], v[98:101]
	v_mfma_f32_16x16x32_bf16 v[86:89], v[158:161], v[190:193], v[86:89]
	v_mfma_f32_16x16x32_bf16 v[82:85], v[166:169], v[190:193], v[82:85]
	v_mfma_f32_16x16x32_bf16 v[70:73], v[158:161], v[198:201], v[70:73]
	v_mfma_f32_16x16x32_bf16 v[66:69], v[166:169], v[198:201], v[66:69]
	s_setprio 0
	s_barrier
	ds_read_b128 v[170:173], v133 offset:16384
	ds_read_b128 v[174:177], v133 offset:17408
	s_mov_b32 m0, s33
	s_nop 0
	buffer_load_dwordx4 v130, s[8:11], s62 offen lds
	ds_read_b128 v[178:181], v133 offset:18432
	ds_read_b128 v[182:185], v133 offset:19456
	s_add_i32 s63, s62, 0x40000
	s_mov_b32 m0, s35
	s_nop 0
	buffer_load_dwordx4 v131, s[8:11], s62 offen lds
	ds_read_b128 v[186:189], v133 offset:20480
	ds_read_b128 v[190:193], v133 offset:21504
	s_nop 0
	s_mov_b32 m0, s36
	s_nop 0
	buffer_load_dwordx4 v130, s[8:11], s63 offen lds
	ds_read_b128 v[194:197], v133 offset:22528
	ds_read_b128 v[198:201], v133 offset:23552
	s_nop 0
	s_mov_b32 m0, s37
	s_nop 0
	buffer_load_dwordx4 v131, s[8:11], s63 offen lds
	s_nop 0
	s_mov_b32 m0, s31
	s_nop 0
	buffer_load_dwordx4 v130, s[12:15], s64 offen lds
	s_nop 0
	s_mov_b32 m0, s40
	s_nop 0
	buffer_load_dwordx4 v131, s[12:15], s64 offen lds
	s_waitcnt vmcnt(8)
	s_waitcnt lgkmcnt(0)
	s_barrier
	s_setprio 1
	s_waitcnt lgkmcnt(7)
	v_mfma_f32_16x16x32_bf16 v[62:65], v[134:137], v[170:173], v[62:65]
	v_mfma_f32_16x16x32_bf16 v[58:61], v[146:149], v[170:173], v[58:61]
	s_waitcnt lgkmcnt(5)
	v_mfma_f32_16x16x32_bf16 v[46:49], v[134:137], v[178:181], v[46:49]
	v_mfma_f32_16x16x32_bf16 v[42:45], v[146:149], v[178:181], v[42:45]
	s_waitcnt lgkmcnt(3)
	v_mfma_f32_16x16x32_bf16 v[30:33], v[134:137], v[186:189], v[30:33]
	v_mfma_f32_16x16x32_bf16 v[26:29], v[146:149], v[186:189], v[26:29]
	s_waitcnt lgkmcnt(1)
	v_mfma_f32_16x16x32_bf16 v[14:17], v[134:137], v[194:197], v[14:17]
	v_mfma_f32_16x16x32_bf16 v[10:13], v[146:149], v[194:197], v[10:13]
	v_mfma_f32_16x16x32_bf16 v[62:65], v[142:145], v[174:177], v[62:65]
	v_mfma_f32_16x16x32_bf16 v[58:61], v[150:153], v[174:177], v[58:61]
	v_mfma_f32_16x16x32_bf16 v[46:49], v[142:145], v[182:185], v[46:49]
	v_mfma_f32_16x16x32_bf16 v[42:45], v[150:153], v[182:185], v[42:45]
	v_mfma_f32_16x16x32_bf16 v[30:33], v[142:145], v[190:193], v[30:33]
	v_mfma_f32_16x16x32_bf16 v[26:29], v[150:153], v[190:193], v[26:29]
	s_waitcnt lgkmcnt(0)
	v_mfma_f32_16x16x32_bf16 v[14:17], v[142:145], v[198:201], v[14:17]
	v_mfma_f32_16x16x32_bf16 v[10:13], v[150:153], v[198:201], v[10:13]
	s_setprio 0
	s_setprio 1
	v_mfma_f32_16x16x32_bf16 v[54:57], v[154:157], v[170:173], v[54:57]
	v_mfma_f32_16x16x32_bf16 v[50:53], v[162:165], v[170:173], v[50:53]
	v_mfma_f32_16x16x32_bf16 v[38:41], v[154:157], v[178:181], v[38:41]
	v_mfma_f32_16x16x32_bf16 v[34:37], v[162:165], v[178:181], v[34:37]
	v_mfma_f32_16x16x32_bf16 v[22:25], v[154:157], v[186:189], v[22:25]
	v_mfma_f32_16x16x32_bf16 v[18:21], v[162:165], v[186:189], v[18:21]
	v_mfma_f32_16x16x32_bf16 v[6:9], v[154:157], v[194:197], v[6:9]
	v_mfma_f32_16x16x32_bf16 v[2:5], v[162:165], v[194:197], v[2:5]
	v_mfma_f32_16x16x32_bf16 v[54:57], v[158:161], v[174:177], v[54:57]
	v_mfma_f32_16x16x32_bf16 v[50:53], v[166:169], v[174:177], v[50:53]
	v_mfma_f32_16x16x32_bf16 v[38:41], v[158:161], v[182:185], v[38:41]
	v_mfma_f32_16x16x32_bf16 v[34:37], v[166:169], v[182:185], v[34:37]
	v_mfma_f32_16x16x32_bf16 v[22:25], v[158:161], v[190:193], v[22:25]
	v_mfma_f32_16x16x32_bf16 v[18:21], v[166:169], v[190:193], v[18:21]
	v_mfma_f32_16x16x32_bf16 v[6:9], v[158:161], v[198:201], v[6:9]
	v_mfma_f32_16x16x32_bf16 v[2:5], v[166:169], v[198:201], v[2:5]
	s_setprio 0
	s_barrier
	v_add_u32_e32 v150, 0x18000, v132
	v_add_u32_e32 v166, 0x1c000, v132
	ds_read_b128 v[134:137], v150
	ds_read_b128 v[142:145], v150 offset:1024
	ds_read_b128 v[146:149], v150 offset:2048
	ds_read_b128 v[150:153], v150 offset:3072
	ds_read_b128 v[154:157], v166
	ds_read_b128 v[158:161], v166 offset:1024
	ds_read_b128 v[162:165], v166 offset:2048
	ds_read_b128 v[166:169], v166 offset:3072
	ds_read_b128 v[170:173], v133 offset:32768
	ds_read_b128 v[174:177], v133 offset:33792
	ds_read_b128 v[178:181], v133 offset:34816
	ds_read_b128 v[182:185], v133 offset:35840
	ds_read_b128 v[186:189], v133 offset:36864
	ds_read_b128 v[190:193], v133 offset:37888
	ds_read_b128 v[194:197], v133 offset:38912
	ds_read_b128 v[198:201], v133 offset:39936
	s_add_i32 s63, s64, 0x40000
	s_mov_b32 m0, s41
	s_nop 0
	buffer_load_dwordx4 v130, s[12:15], s63 offen lds
	s_nop 0
	s_mov_b32 m0, s42
	s_nop 0
	buffer_load_dwordx4 v131, s[12:15], s63 offen lds
	s_waitcnt vmcnt(8)
	s_waitcnt lgkmcnt(0)
	s_barrier
	s_setprio 1
	s_waitcnt lgkmcnt(7)
	v_mfma_f32_16x16x32_bf16 v[138:141], v[134:137], v[170:173], v[138:141]
	v_mfma_f32_16x16x32_bf16 v[126:129], v[146:149], v[170:173], v[126:129]
	s_waitcnt lgkmcnt(5)
	v_mfma_f32_16x16x32_bf16 v[110:113], v[134:137], v[178:181], v[110:113]
	v_mfma_f32_16x16x32_bf16 v[106:109], v[146:149], v[178:181], v[106:109]
	s_waitcnt lgkmcnt(3)
	v_mfma_f32_16x16x32_bf16 v[94:97], v[134:137], v[186:189], v[94:97]
	v_mfma_f32_16x16x32_bf16 v[90:93], v[146:149], v[186:189], v[90:93]
	s_waitcnt lgkmcnt(1)
	v_mfma_f32_16x16x32_bf16 v[78:81], v[134:137], v[194:197], v[78:81]
	v_mfma_f32_16x16x32_bf16 v[74:77], v[146:149], v[194:197], v[74:77]
	v_mfma_f32_16x16x32_bf16 v[138:141], v[142:145], v[174:177], v[138:141]
	v_mfma_f32_16x16x32_bf16 v[126:129], v[150:153], v[174:177], v[126:129]
	v_mfma_f32_16x16x32_bf16 v[110:113], v[142:145], v[182:185], v[110:113]
	v_mfma_f32_16x16x32_bf16 v[106:109], v[150:153], v[182:185], v[106:109]
	v_mfma_f32_16x16x32_bf16 v[94:97], v[142:145], v[190:193], v[94:97]
	v_mfma_f32_16x16x32_bf16 v[90:93], v[150:153], v[190:193], v[90:93]
	s_waitcnt lgkmcnt(0)
	v_mfma_f32_16x16x32_bf16 v[78:81], v[142:145], v[198:201], v[78:81]
	v_mfma_f32_16x16x32_bf16 v[74:77], v[150:153], v[198:201], v[74:77]
	s_setprio 0
	s_setprio 1
	v_mfma_f32_16x16x32_bf16 v[118:121], v[154:157], v[170:173], v[118:121]
	v_mfma_f32_16x16x32_bf16 v[114:117], v[162:165], v[170:173], v[114:117]
	v_mfma_f32_16x16x32_bf16 v[102:105], v[154:157], v[178:181], v[102:105]
	v_mfma_f32_16x16x32_bf16 v[98:101], v[162:165], v[178:181], v[98:101]
	v_mfma_f32_16x16x32_bf16 v[86:89], v[154:157], v[186:189], v[86:89]
	v_mfma_f32_16x16x32_bf16 v[82:85], v[162:165], v[186:189], v[82:85]
	v_mfma_f32_16x16x32_bf16 v[70:73], v[154:157], v[194:197], v[70:73]
	v_mfma_f32_16x16x32_bf16 v[66:69], v[162:165], v[194:197], v[66:69]
	v_mfma_f32_16x16x32_bf16 v[118:121], v[158:161], v[174:177], v[118:121]
	v_mfma_f32_16x16x32_bf16 v[114:117], v[166:169], v[174:177], v[114:117]
	v_mfma_f32_16x16x32_bf16 v[102:105], v[158:161], v[182:185], v[102:105]
	v_mfma_f32_16x16x32_bf16 v[98:101], v[166:169], v[182:185], v[98:101]
	v_mfma_f32_16x16x32_bf16 v[86:89], v[158:161], v[190:193], v[86:89]
	v_mfma_f32_16x16x32_bf16 v[82:85], v[166:169], v[190:193], v[82:85]
	v_mfma_f32_16x16x32_bf16 v[70:73], v[158:161], v[198:201], v[70:73]
	v_mfma_f32_16x16x32_bf16 v[66:69], v[166:169], v[198:201], v[66:69]
	s_setprio 0
	s_barrier
	ds_read_b128 v[170:173], v133 offset:49152
	ds_read_b128 v[174:177], v133 offset:50176
	s_or_b32 s63, s62, 0x80
	s_mov_b32 m0, s43
	s_nop 0
	buffer_load_dwordx4 v130, s[8:11], s63 offen lds
	ds_read_b128 v[178:181], v133 offset:51200
	ds_read_b128 v[182:185], v133 offset:52224
	s_add_i32 s62, s62, 0x40080
	s_mov_b32 m0, s44
	s_nop 0
	buffer_load_dwordx4 v131, s[8:11], s63 offen lds
	ds_read_b128 v[186:189], v133 offset:53248
	ds_read_b128 v[190:193], v133 offset:54272
	s_nop 0
	s_mov_b32 m0, s47
	s_nop 0
	buffer_load_dwordx4 v130, s[8:11], s62 offen lds
	ds_read_b128 v[194:197], v133 offset:55296
	ds_read_b128 v[198:201], v133 offset:56320
	s_nop 0
	s_mov_b32 m0, s48
	s_nop 0
	buffer_load_dwordx4 v131, s[8:11], s62 offen lds
	s_nop 0
	s_mov_b32 m0, s45
	s_nop 0
	buffer_load_dwordx4 v130, s[12:15], s61 offen lds
	s_nop 0
	s_mov_b32 m0, s46
	s_nop 0
	buffer_load_dwordx4 v131, s[12:15], s61 offen lds
	s_waitcnt vmcnt(8)
	s_waitcnt lgkmcnt(0)
	s_barrier
	s_setprio 1
	s_waitcnt lgkmcnt(7)
	v_mfma_f32_16x16x32_bf16 v[62:65], v[134:137], v[170:173], v[62:65]
	v_mfma_f32_16x16x32_bf16 v[58:61], v[146:149], v[170:173], v[58:61]
	s_waitcnt lgkmcnt(5)
	v_mfma_f32_16x16x32_bf16 v[46:49], v[134:137], v[178:181], v[46:49]
	v_mfma_f32_16x16x32_bf16 v[42:45], v[146:149], v[178:181], v[42:45]
	s_waitcnt lgkmcnt(3)
	v_mfma_f32_16x16x32_bf16 v[30:33], v[134:137], v[186:189], v[30:33]
	v_mfma_f32_16x16x32_bf16 v[26:29], v[146:149], v[186:189], v[26:29]
	s_waitcnt lgkmcnt(1)
	v_mfma_f32_16x16x32_bf16 v[14:17], v[134:137], v[194:197], v[14:17]
	v_mfma_f32_16x16x32_bf16 v[10:13], v[146:149], v[194:197], v[10:13]
	v_mfma_f32_16x16x32_bf16 v[62:65], v[142:145], v[174:177], v[62:65]
	v_mfma_f32_16x16x32_bf16 v[58:61], v[150:153], v[174:177], v[58:61]
	v_mfma_f32_16x16x32_bf16 v[46:49], v[142:145], v[182:185], v[46:49]
	v_mfma_f32_16x16x32_bf16 v[42:45], v[150:153], v[182:185], v[42:45]
	v_mfma_f32_16x16x32_bf16 v[30:33], v[142:145], v[190:193], v[30:33]
	v_mfma_f32_16x16x32_bf16 v[26:29], v[150:153], v[190:193], v[26:29]
	s_waitcnt lgkmcnt(0)
	v_mfma_f32_16x16x32_bf16 v[14:17], v[142:145], v[198:201], v[14:17]
	v_mfma_f32_16x16x32_bf16 v[10:13], v[150:153], v[198:201], v[10:13]
	s_setprio 0
	s_setprio 1
	v_mfma_f32_16x16x32_bf16 v[54:57], v[154:157], v[170:173], v[54:57]
	v_mfma_f32_16x16x32_bf16 v[50:53], v[162:165], v[170:173], v[50:53]
	v_mfma_f32_16x16x32_bf16 v[38:41], v[154:157], v[178:181], v[38:41]
	v_mfma_f32_16x16x32_bf16 v[34:37], v[162:165], v[178:181], v[34:37]
	v_mfma_f32_16x16x32_bf16 v[22:25], v[154:157], v[186:189], v[22:25]
	v_mfma_f32_16x16x32_bf16 v[18:21], v[162:165], v[186:189], v[18:21]
	v_mfma_f32_16x16x32_bf16 v[6:9], v[154:157], v[194:197], v[6:9]
	v_mfma_f32_16x16x32_bf16 v[2:5], v[162:165], v[194:197], v[2:5]
	v_mfma_f32_16x16x32_bf16 v[54:57], v[158:161], v[174:177], v[54:57]
	v_mfma_f32_16x16x32_bf16 v[50:53], v[166:169], v[174:177], v[50:53]
	v_mfma_f32_16x16x32_bf16 v[38:41], v[158:161], v[182:185], v[38:41]
	v_mfma_f32_16x16x32_bf16 v[34:37], v[166:169], v[182:185], v[34:37]
	v_mfma_f32_16x16x32_bf16 v[22:25], v[158:161], v[190:193], v[22:25]
	v_mfma_f32_16x16x32_bf16 v[18:21], v[166:169], v[190:193], v[18:21]
	v_mfma_f32_16x16x32_bf16 v[6:9], v[158:161], v[198:201], v[6:9]
	v_mfma_f32_16x16x32_bf16 v[2:5], v[166:169], v[198:201], v[2:5]
	s_setprio 0
	s_barrier
	s_add_i32 s59, s59, 2
	s_addk_i32 s60, 0x100
	s_cmp_gt_u32 s59, 13
	s_cbranch_scc0 .LBB0_223
	s_andn2_b64 vcc, exec, s[6:7]
	s_cbranch_vccnz .LBB0_215
	v_mov_b32_e32 v2, 0
	s_mov_b32 s18, s52
	s_mov_b32 s29, s53
	s_mov_b32 s34, s3
	s_mov_b32 s39, s2
	s_mov_b32 s51, s54
	v_mov_b32_e32 v3, v2
	v_mov_b32_e32 v4, v2
	v_mov_b32_e32 v5, v2
	v_mov_b32_e32 v6, v2
	v_mov_b32_e32 v7, v2
	v_mov_b32_e32 v8, v2
	v_mov_b32_e32 v9, v2
	v_mov_b32_e32 v18, v2
	v_mov_b32_e32 v19, v2
	v_mov_b32_e32 v20, v2
	v_mov_b32_e32 v21, v2
	v_mov_b32_e32 v22, v2
	v_mov_b32_e32 v23, v2
	v_mov_b32_e32 v24, v2
	v_mov_b32_e32 v25, v2
	v_mov_b32_e32 v34, v2
	v_mov_b32_e32 v35, v2
	v_mov_b32_e32 v36, v2
	v_mov_b32_e32 v37, v2
	v_mov_b32_e32 v38, v2
	v_mov_b32_e32 v39, v2
	v_mov_b32_e32 v40, v2
	v_mov_b32_e32 v41, v2
	v_mov_b32_e32 v50, v2
	v_mov_b32_e32 v51, v2
	v_mov_b32_e32 v52, v2
	v_mov_b32_e32 v53, v2
	v_mov_b32_e32 v54, v2
	v_mov_b32_e32 v55, v2
	v_mov_b32_e32 v56, v2
	v_mov_b32_e32 v57, v2
	v_mov_b32_e32 v10, v2
	v_mov_b32_e32 v11, v2
	v_mov_b32_e32 v12, v2
	v_mov_b32_e32 v13, v2
	v_mov_b32_e32 v14, v2
	v_mov_b32_e32 v15, v2
	v_mov_b32_e32 v16, v2
	v_mov_b32_e32 v17, v2
	v_mov_b32_e32 v26, v2
	v_mov_b32_e32 v27, v2
	v_mov_b32_e32 v28, v2
	v_mov_b32_e32 v29, v2
	v_mov_b32_e32 v30, v2
	v_mov_b32_e32 v31, v2
	v_mov_b32_e32 v32, v2
	v_mov_b32_e32 v33, v2
	v_mov_b32_e32 v42, v2
	v_mov_b32_e32 v43, v2
	v_mov_b32_e32 v44, v2
	v_mov_b32_e32 v45, v2
	v_mov_b32_e32 v46, v2
	v_mov_b32_e32 v47, v2
	v_mov_b32_e32 v48, v2
	v_mov_b32_e32 v49, v2
	v_mov_b32_e32 v58, v2
	v_mov_b32_e32 v59, v2
	v_mov_b32_e32 v60, v2
	v_mov_b32_e32 v61, v2
	v_mov_b32_e32 v62, v2
	v_mov_b32_e32 v63, v2
	v_mov_b32_e32 v64, v2
	v_mov_b32_e32 v65, v2
	v_mov_b32_e32 v66, v2
	v_mov_b32_e32 v67, v2
	v_mov_b32_e32 v68, v2
	v_mov_b32_e32 v69, v2
	v_mov_b32_e32 v70, v2
	v_mov_b32_e32 v71, v2
	v_mov_b32_e32 v72, v2
	v_mov_b32_e32 v73, v2
	v_mov_b32_e32 v82, v2
	v_mov_b32_e32 v83, v2
	v_mov_b32_e32 v84, v2
	v_mov_b32_e32 v85, v2
	v_mov_b32_e32 v86, v2
	v_mov_b32_e32 v87, v2
	v_mov_b32_e32 v88, v2
	v_mov_b32_e32 v89, v2
	v_mov_b32_e32 v98, v2
	v_mov_b32_e32 v99, v2
	v_mov_b32_e32 v100, v2
	v_mov_b32_e32 v101, v2
	v_mov_b32_e32 v102, v2
	v_mov_b32_e32 v103, v2
	v_mov_b32_e32 v104, v2
	v_mov_b32_e32 v105, v2
	v_mov_b32_e32 v114, v2
	v_mov_b32_e32 v115, v2
	v_mov_b32_e32 v116, v2
	v_mov_b32_e32 v117, v2
	v_mov_b32_e32 v118, v2
	v_mov_b32_e32 v119, v2
	v_mov_b32_e32 v120, v2
	v_mov_b32_e32 v121, v2
	v_mov_b32_e32 v74, v2
	v_mov_b32_e32 v75, v2
	v_mov_b32_e32 v76, v2
	v_mov_b32_e32 v77, v2
	v_mov_b32_e32 v78, v2
	v_mov_b32_e32 v79, v2
	v_mov_b32_e32 v80, v2
	v_mov_b32_e32 v81, v2
	v_mov_b32_e32 v90, v2
	v_mov_b32_e32 v91, v2
	v_mov_b32_e32 v92, v2
	v_mov_b32_e32 v93, v2
	v_mov_b32_e32 v94, v2
	v_mov_b32_e32 v95, v2
	v_mov_b32_e32 v96, v2
	v_mov_b32_e32 v97, v2
	v_mov_b32_e32 v106, v2
	v_mov_b32_e32 v107, v2
	v_mov_b32_e32 v108, v2
	v_mov_b32_e32 v109, v2
	v_mov_b32_e32 v110, v2
	v_mov_b32_e32 v111, v2
	v_mov_b32_e32 v112, v2
	v_mov_b32_e32 v113, v2
	v_mov_b32_e32 v126, v2
	v_mov_b32_e32 v127, v2
	v_mov_b32_e32 v128, v2
	v_mov_b32_e32 v129, v2
	v_mov_b32_e32 v138, v2
	v_mov_b32_e32 v139, v2
	v_mov_b32_e32 v140, v2
	v_mov_b32_e32 v141, v2
	s_branch .LBB0_215

.LBB0_353:
	ds_read_b128 v[136:139], v153
	ds_read_b128 v[140:143], v153 offset:1024
	ds_read_b128 v[158:161], v153 offset:2048
	ds_read_b128 v[162:165], v153 offset:3072
	ds_read_b128 v[166:169], v154
	ds_read_b128 v[170:173], v154 offset:1024
	ds_read_b128 v[174:177], v154 offset:2048
	ds_read_b128 v[178:181], v154 offset:3072
	s_add_i32 s66, s63, 0xfffe0080
	s_cmp_eq_u32 s65, 4
	s_cselect_b32 s68, s1, s66
	s_cselect_b32 s67, s62, s64
	s_or_b32 s66, s68, 0x80
	ds_read_b128 v[182:185], v155
	ds_read_b128 v[186:189], v155 offset:1024
	ds_read_b128 v[190:193], v155 offset:2048
	ds_read_b128 v[194:197], v155 offset:3072
	ds_read_b128 v[198:201], v155 offset:4096
	ds_read_b128 v[202:205], v155 offset:5120
	ds_read_b128 v[206:209], v155 offset:6144
	ds_read_b128 v[210:213], v155 offset:7168
	s_mov_b32 m0, s48
	s_nop 0
	buffer_load_dwordx4 v147, s[12:15], s63 offen lds
	s_nop 0
	s_mov_b32 m0, s49
	s_nop 0
	buffer_load_dwordx4 v148, s[12:15], s63 offen lds
	s_waitcnt vmcnt(8)
	s_waitcnt lgkmcnt(0)
	s_barrier
	s_setprio 1
	s_waitcnt lgkmcnt(0)
	v_mfma_i32_16x16x64_i8 v[126:129], v[136:139], v[182:185], v[126:129]
	v_mfma_i32_16x16x64_i8 v[122:125], v[158:161], v[182:185], v[122:125]
	v_mfma_i32_16x16x64_i8 v[118:121], v[136:139], v[190:193], v[118:121]
	v_mfma_i32_16x16x64_i8 v[114:117], v[158:161], v[190:193], v[114:117]
	v_mfma_i32_16x16x64_i8 v[110:113], v[136:139], v[198:201], v[110:113]
	v_mfma_i32_16x16x64_i8 v[106:109], v[158:161], v[198:201], v[106:109]
	v_mfma_i32_16x16x64_i8 v[102:105], v[136:139], v[206:209], v[102:105]
	v_mfma_i32_16x16x64_i8 v[98:101], v[158:161], v[206:209], v[98:101]
	v_mfma_i32_16x16x64_i8 v[126:129], v[140:143], v[186:189], v[126:129]
	v_mfma_i32_16x16x64_i8 v[122:125], v[162:165], v[186:189], v[122:125]
	v_mfma_i32_16x16x64_i8 v[118:121], v[140:143], v[194:197], v[118:121]
	v_mfma_i32_16x16x64_i8 v[114:117], v[162:165], v[194:197], v[114:117]
	v_mfma_i32_16x16x64_i8 v[110:113], v[140:143], v[202:205], v[110:113]
	v_mfma_i32_16x16x64_i8 v[106:109], v[162:165], v[202:205], v[106:109]
	v_mfma_i32_16x16x64_i8 v[102:105], v[140:143], v[210:213], v[102:105]
	v_mfma_i32_16x16x64_i8 v[98:101], v[162:165], v[210:213], v[98:101]
	s_setprio 0
	s_setprio 1
	v_mfma_i32_16x16x64_i8 v[94:97], v[166:169], v[182:185], v[94:97]
	v_mfma_i32_16x16x64_i8 v[90:93], v[174:177], v[182:185], v[90:93]
	v_mfma_i32_16x16x64_i8 v[86:89], v[166:169], v[190:193], v[86:89]
	v_mfma_i32_16x16x64_i8 v[82:85], v[174:177], v[190:193], v[82:85]
	v_mfma_i32_16x16x64_i8 v[78:81], v[166:169], v[198:201], v[78:81]
	v_mfma_i32_16x16x64_i8 v[74:77], v[174:177], v[198:201], v[74:77]
	v_mfma_i32_16x16x64_i8 v[70:73], v[166:169], v[206:209], v[70:73]
	v_mfma_i32_16x16x64_i8 v[66:69], v[174:177], v[206:209], v[66:69]
	v_mfma_i32_16x16x64_i8 v[94:97], v[170:173], v[186:189], v[94:97]
	v_mfma_i32_16x16x64_i8 v[90:93], v[178:181], v[186:189], v[90:93]
	v_mfma_i32_16x16x64_i8 v[86:89], v[170:173], v[194:197], v[86:89]
	v_mfma_i32_16x16x64_i8 v[82:85], v[178:181], v[194:197], v[82:85]
	v_mfma_i32_16x16x64_i8 v[78:81], v[170:173], v[202:205], v[78:81]
	v_mfma_i32_16x16x64_i8 v[74:77], v[178:181], v[202:205], v[74:77]
	v_mfma_i32_16x16x64_i8 v[70:73], v[170:173], v[210:213], v[70:73]
	v_mfma_i32_16x16x64_i8 v[66:69], v[178:181], v[210:213], v[66:69]
	s_setprio 0
	s_barrier
	ds_read_b128 v[182:185], v155 offset:16384
	ds_read_b128 v[186:189], v155 offset:17408
	s_mov_b32 m0, s34
	s_nop 0
	buffer_load_dwordx4 v145, s[8:11], s67 offen lds
	ds_read_b128 v[190:193], v155 offset:18432
	ds_read_b128 v[194:197], v155 offset:19456
	s_add_i32 s69, s67, 0x20000
	s_mov_b32 m0, s35
	s_nop 0
	buffer_load_dwordx4 v146, s[8:11], s67 offen lds
	ds_read_b128 v[198:201], v155 offset:20480
	ds_read_b128 v[202:205], v155 offset:21504
	s_nop 0
	s_mov_b32 m0, s36
	s_nop 0
	buffer_load_dwordx4 v145, s[8:11], s69 offen lds
	ds_read_b128 v[206:209], v155 offset:22528
	ds_read_b128 v[210:213], v155 offset:23552
	s_nop 0
	s_mov_b32 m0, s37
	s_nop 0
	buffer_load_dwordx4 v146, s[8:11], s69 offen lds
	s_nop 0
	s_mov_b32 m0, s33
	s_nop 0
	buffer_load_dwordx4 v147, s[12:15], s68 offen lds
	s_nop 0
	s_mov_b32 m0, s2
	s_nop 0
	buffer_load_dwordx4 v148, s[12:15], s68 offen lds
	s_waitcnt vmcnt(8)
	s_waitcnt lgkmcnt(0)
	s_barrier
	s_setprio 1
	s_waitcnt lgkmcnt(0)
	v_mfma_i32_16x16x64_i8 v[62:65], v[136:139], v[182:185], v[62:65]
	v_mfma_i32_16x16x64_i8 v[58:61], v[158:161], v[182:185], v[58:61]
	v_mfma_i32_16x16x64_i8 v[54:57], v[136:139], v[190:193], v[54:57]
	v_mfma_i32_16x16x64_i8 v[50:53], v[158:161], v[190:193], v[50:53]
	v_mfma_i32_16x16x64_i8 v[46:49], v[136:139], v[198:201], v[46:49]
	v_mfma_i32_16x16x64_i8 v[42:45], v[158:161], v[198:201], v[42:45]
	v_mfma_i32_16x16x64_i8 v[38:41], v[136:139], v[206:209], v[38:41]
	v_mfma_i32_16x16x64_i8 v[34:37], v[158:161], v[206:209], v[34:37]
	v_mfma_i32_16x16x64_i8 v[62:65], v[140:143], v[186:189], v[62:65]
	v_mfma_i32_16x16x64_i8 v[58:61], v[162:165], v[186:189], v[58:61]
	v_mfma_i32_16x16x64_i8 v[54:57], v[140:143], v[194:197], v[54:57]
	v_mfma_i32_16x16x64_i8 v[50:53], v[162:165], v[194:197], v[50:53]
	v_mfma_i32_16x16x64_i8 v[46:49], v[140:143], v[202:205], v[46:49]
	v_mfma_i32_16x16x64_i8 v[42:45], v[162:165], v[202:205], v[42:45]
	v_mfma_i32_16x16x64_i8 v[38:41], v[140:143], v[210:213], v[38:41]
	v_mfma_i32_16x16x64_i8 v[34:37], v[162:165], v[210:213], v[34:37]
	s_setprio 0
	s_setprio 1
	v_mfma_i32_16x16x64_i8 v[30:33], v[166:169], v[182:185], v[30:33]
	v_mfma_i32_16x16x64_i8 v[26:29], v[174:177], v[182:185], v[26:29]
	v_mfma_i32_16x16x64_i8 v[22:25], v[166:169], v[190:193], v[22:25]
	v_mfma_i32_16x16x64_i8 v[18:21], v[174:177], v[190:193], v[18:21]
	v_mfma_i32_16x16x64_i8 v[14:17], v[166:169], v[198:201], v[14:17]
	v_mfma_i32_16x16x64_i8 v[10:13], v[174:177], v[198:201], v[10:13]
	v_mfma_i32_16x16x64_i8 v[6:9], v[166:169], v[206:209], v[6:9]
	v_mfma_i32_16x16x64_i8 v[2:5], v[174:177], v[206:209], v[2:5]
	v_mfma_i32_16x16x64_i8 v[30:33], v[170:173], v[186:189], v[30:33]
	v_mfma_i32_16x16x64_i8 v[26:29], v[178:181], v[186:189], v[26:29]
	v_mfma_i32_16x16x64_i8 v[22:25], v[170:173], v[194:197], v[22:25]
	v_mfma_i32_16x16x64_i8 v[18:21], v[178:181], v[194:197], v[18:21]
	v_mfma_i32_16x16x64_i8 v[14:17], v[170:173], v[202:205], v[14:17]
	v_mfma_i32_16x16x64_i8 v[10:13], v[178:181], v[202:205], v[10:13]
	v_mfma_i32_16x16x64_i8 v[6:9], v[170:173], v[210:213], v[6:9]
	v_mfma_i32_16x16x64_i8 v[2:5], v[178:181], v[210:213], v[2:5]
	s_setprio 0
	s_barrier
	ds_read_b128 v[136:139], v156
	ds_read_b128 v[140:143], v156 offset:1024
	ds_read_b128 v[158:161], v156 offset:2048
	ds_read_b128 v[162:165], v156 offset:3072
	ds_read_b128 v[166:169], v157
	ds_read_b128 v[170:173], v157 offset:1024
	ds_read_b128 v[174:177], v157 offset:2048
	ds_read_b128 v[178:181], v157 offset:3072
	ds_read_b128 v[182:185], v155 offset:32768
	ds_read_b128 v[186:189], v155 offset:33792
	ds_read_b128 v[190:193], v155 offset:34816
	ds_read_b128 v[194:197], v155 offset:35840
	ds_read_b128 v[198:201], v155 offset:36864
	ds_read_b128 v[202:205], v155 offset:37888
	ds_read_b128 v[206:209], v155 offset:38912
	ds_read_b128 v[210:213], v155 offset:39936
	s_add_i32 s68, s68, 0x20000
	s_mov_b32 m0, s3
	s_nop 0
	buffer_load_dwordx4 v147, s[12:15], s68 offen lds
	s_nop 0
	s_mov_b32 m0, s38
	s_nop 0
	buffer_load_dwordx4 v148, s[12:15], s68 offen lds
	s_waitcnt vmcnt(8)
	s_waitcnt lgkmcnt(0)
	s_barrier
	s_setprio 1
	s_waitcnt lgkmcnt(0)
	v_mfma_i32_16x16x64_i8 v[126:129], v[136:139], v[182:185], v[126:129]
	v_mfma_i32_16x16x64_i8 v[122:125], v[158:161], v[182:185], v[122:125]
	v_mfma_i32_16x16x64_i8 v[118:121], v[136:139], v[190:193], v[118:121]
	v_mfma_i32_16x16x64_i8 v[114:117], v[158:161], v[190:193], v[114:117]
	v_mfma_i32_16x16x64_i8 v[110:113], v[136:139], v[198:201], v[110:113]
	v_mfma_i32_16x16x64_i8 v[106:109], v[158:161], v[198:201], v[106:109]
	v_mfma_i32_16x16x64_i8 v[102:105], v[136:139], v[206:209], v[102:105]
	v_mfma_i32_16x16x64_i8 v[98:101], v[158:161], v[206:209], v[98:101]
	v_mfma_i32_16x16x64_i8 v[126:129], v[140:143], v[186:189], v[126:129]
	v_mfma_i32_16x16x64_i8 v[122:125], v[162:165], v[186:189], v[122:125]
	v_mfma_i32_16x16x64_i8 v[118:121], v[140:143], v[194:197], v[118:121]
	v_mfma_i32_16x16x64_i8 v[114:117], v[162:165], v[194:197], v[114:117]
	v_mfma_i32_16x16x64_i8 v[110:113], v[140:143], v[202:205], v[110:113]
	v_mfma_i32_16x16x64_i8 v[106:109], v[162:165], v[202:205], v[106:109]
	v_mfma_i32_16x16x64_i8 v[102:105], v[140:143], v[210:213], v[102:105]
	v_mfma_i32_16x16x64_i8 v[98:101], v[162:165], v[210:213], v[98:101]
	s_setprio 0
	s_setprio 1
	v_mfma_i32_16x16x64_i8 v[94:97], v[166:169], v[182:185], v[94:97]
	v_mfma_i32_16x16x64_i8 v[90:93], v[174:177], v[182:185], v[90:93]
	v_mfma_i32_16x16x64_i8 v[86:89], v[166:169], v[190:193], v[86:89]
	v_mfma_i32_16x16x64_i8 v[82:85], v[174:177], v[190:193], v[82:85]
	v_mfma_i32_16x16x64_i8 v[78:81], v[166:169], v[198:201], v[78:81]
	v_mfma_i32_16x16x64_i8 v[74:77], v[174:177], v[198:201], v[74:77]
	v_mfma_i32_16x16x64_i8 v[70:73], v[166:169], v[206:209], v[70:73]
	v_mfma_i32_16x16x64_i8 v[66:69], v[174:177], v[206:209], v[66:69]
	v_mfma_i32_16x16x64_i8 v[94:97], v[170:173], v[186:189], v[94:97]
	v_mfma_i32_16x16x64_i8 v[90:93], v[178:181], v[186:189], v[90:93]
	v_mfma_i32_16x16x64_i8 v[86:89], v[170:173], v[194:197], v[86:89]
	v_mfma_i32_16x16x64_i8 v[82:85], v[178:181], v[194:197], v[82:85]
	v_mfma_i32_16x16x64_i8 v[78:81], v[170:173], v[202:205], v[78:81]
	v_mfma_i32_16x16x64_i8 v[74:77], v[178:181], v[202:205], v[74:77]
	v_mfma_i32_16x16x64_i8 v[70:73], v[170:173], v[210:213], v[70:73]
	v_mfma_i32_16x16x64_i8 v[66:69], v[178:181], v[210:213], v[66:69]
	s_setprio 0
	s_barrier
	ds_read_b128 v[182:185], v155 offset:49152
	ds_read_b128 v[186:189], v155 offset:50176
	s_or_b32 s68, s67, 0x80
	s_mov_b32 m0, s41
	s_nop 0
	buffer_load_dwordx4 v145, s[8:11], s68 offen lds
	ds_read_b128 v[190:193], v155 offset:51200
	ds_read_b128 v[194:197], v155 offset:52224
	s_add_i32 s67, s67, 0x20080
	s_mov_b32 m0, s42
	s_nop 0
	buffer_load_dwordx4 v146, s[8:11], s68 offen lds
	ds_read_b128 v[198:201], v155 offset:53248
	ds_read_b128 v[202:205], v155 offset:54272
	s_nop 0
	s_mov_b32 m0, s45
	s_nop 0
	buffer_load_dwordx4 v145, s[8:11], s67 offen lds
	ds_read_b128 v[206:209], v155 offset:55296
	ds_read_b128 v[210:213], v155 offset:56320
	s_nop 0
	s_mov_b32 m0, s46
	s_nop 0
	buffer_load_dwordx4 v146, s[8:11], s67 offen lds
	s_nop 0
	s_mov_b32 m0, s43
	s_nop 0
	buffer_load_dwordx4 v147, s[12:15], s66 offen lds
	s_nop 0
	s_mov_b32 m0, s44
	s_nop 0
	buffer_load_dwordx4 v148, s[12:15], s66 offen lds
	s_waitcnt vmcnt(8)
	s_waitcnt lgkmcnt(0)
	s_barrier
	s_setprio 1
	s_waitcnt lgkmcnt(0)
	v_mfma_i32_16x16x64_i8 v[62:65], v[136:139], v[182:185], v[62:65]
	v_mfma_i32_16x16x64_i8 v[58:61], v[158:161], v[182:185], v[58:61]
	v_mfma_i32_16x16x64_i8 v[54:57], v[136:139], v[190:193], v[54:57]
	v_mfma_i32_16x16x64_i8 v[50:53], v[158:161], v[190:193], v[50:53]
	v_mfma_i32_16x16x64_i8 v[46:49], v[136:139], v[198:201], v[46:49]
	v_mfma_i32_16x16x64_i8 v[42:45], v[158:161], v[198:201], v[42:45]
	v_mfma_i32_16x16x64_i8 v[38:41], v[136:139], v[206:209], v[38:41]
	v_mfma_i32_16x16x64_i8 v[34:37], v[158:161], v[206:209], v[34:37]
	v_mfma_i32_16x16x64_i8 v[62:65], v[140:143], v[186:189], v[62:65]
	v_mfma_i32_16x16x64_i8 v[58:61], v[162:165], v[186:189], v[58:61]
	v_mfma_i32_16x16x64_i8 v[54:57], v[140:143], v[194:197], v[54:57]
	v_mfma_i32_16x16x64_i8 v[50:53], v[162:165], v[194:197], v[50:53]
	v_mfma_i32_16x16x64_i8 v[46:49], v[140:143], v[202:205], v[46:49]
	v_mfma_i32_16x16x64_i8 v[42:45], v[162:165], v[202:205], v[42:45]
	v_mfma_i32_16x16x64_i8 v[38:41], v[140:143], v[210:213], v[38:41]
	v_mfma_i32_16x16x64_i8 v[34:37], v[162:165], v[210:213], v[34:37]
	s_setprio 0
	s_setprio 1
	v_mfma_i32_16x16x64_i8 v[30:33], v[166:169], v[182:185], v[30:33]
	v_mfma_i32_16x16x64_i8 v[26:29], v[174:177], v[182:185], v[26:29]
	v_mfma_i32_16x16x64_i8 v[22:25], v[166:169], v[190:193], v[22:25]
	v_mfma_i32_16x16x64_i8 v[18:21], v[174:177], v[190:193], v[18:21]
	v_mfma_i32_16x16x64_i8 v[14:17], v[166:169], v[198:201], v[14:17]
	v_mfma_i32_16x16x64_i8 v[10:13], v[174:177], v[198:201], v[10:13]
	v_mfma_i32_16x16x64_i8 v[6:9], v[166:169], v[206:209], v[6:9]
	v_mfma_i32_16x16x64_i8 v[2:5], v[174:177], v[206:209], v[2:5]
	v_mfma_i32_16x16x64_i8 v[30:33], v[170:173], v[186:189], v[30:33]
	v_mfma_i32_16x16x64_i8 v[26:29], v[178:181], v[186:189], v[26:29]
	v_mfma_i32_16x16x64_i8 v[22:25], v[170:173], v[194:197], v[22:25]
	v_mfma_i32_16x16x64_i8 v[18:21], v[178:181], v[194:197], v[18:21]
	v_mfma_i32_16x16x64_i8 v[14:17], v[170:173], v[202:205], v[14:17]
	v_mfma_i32_16x16x64_i8 v[10:13], v[178:181], v[202:205], v[10:13]
	v_mfma_i32_16x16x64_i8 v[6:9], v[170:173], v[210:213], v[6:9]
	v_mfma_i32_16x16x64_i8 v[2:5], v[178:181], v[210:213], v[2:5]
	s_setprio 0
	s_barrier
	s_add_i32 s65, s65, 2
	s_addk_i32 s63, 0x100
	s_addk_i32 s64, 0x100
	s_cmp_gt_u32 s65, 5
	s_cbranch_scc0 .LBB0_353
	s_and_b64 vcc, exec, s[24:25]
	s_cbranch_vccz .LBB0_356
	s_barrier

.LBB0_467:
	v_add_u32_e32 v147, 0x10000, v132
	ds_read_b128 v[138:141], v147
	ds_read_b128 v[142:145], v147 offset:1024
	ds_read_b128 v[148:151], v147 offset:2048
	ds_read_b128 v[152:155], v147 offset:3072
	v_add_u32_e32 v147, 0x14000, v132
	ds_read_b128 v[156:159], v147
	ds_read_b128 v[160:163], v147 offset:1024
	ds_read_b128 v[164:167], v147 offset:2048
	ds_read_b128 v[168:171], v147 offset:3072
	s_add_i32 s59, s3, s1
	s_add_i32 s58, s33, s1
	s_add_i32 s55, s59, 0x1600
	s_addk_i32 s58, 0x1600
	s_cmp_eq_u32 s1, 0
	s_cselect_b32 s60, s53, s55
	s_cselect_b32 s58, s54, s58
	s_add_i32 s55, s60, 0x80
	ds_read_b128 v[172:175], v133
	ds_read_b128 v[176:179], v133 offset:1024
	ds_read_b128 v[180:183], v133 offset:2048
	ds_read_b128 v[184:187], v133 offset:3072
	ds_read_b128 v[188:191], v133 offset:4096
	ds_read_b128 v[192:195], v133 offset:5120
	ds_read_b128 v[196:199], v133 offset:6144
	ds_read_b128 v[200:203], v133 offset:7168
	s_add_i32 s59, s59, 0xb1580
	s_mov_b32 m0, s46
	s_nop 0
	buffer_load_dwordx4 v130, s[12:15], s59 offen lds
	s_nop 0
	s_mov_b32 m0, s47
	s_nop 0
	buffer_load_dwordx4 v131, s[12:15], s59 offen lds
	s_waitcnt vmcnt(8)
	s_waitcnt lgkmcnt(0)
	s_barrier
	s_setprio 1
	s_waitcnt lgkmcnt(7)
	v_mfma_f32_16x16x32_bf16 v[134:137], v[138:141], v[172:175], v[134:137]
	v_mfma_f32_16x16x32_bf16 v[122:125], v[148:151], v[172:175], v[122:125]
	s_waitcnt lgkmcnt(5)
	v_mfma_f32_16x16x32_bf16 v[110:113], v[138:141], v[180:183], v[110:113]
	v_mfma_f32_16x16x32_bf16 v[106:109], v[148:151], v[180:183], v[106:109]
	s_waitcnt lgkmcnt(3)
	v_mfma_f32_16x16x32_bf16 v[94:97], v[138:141], v[188:191], v[94:97]
	v_mfma_f32_16x16x32_bf16 v[90:93], v[148:151], v[188:191], v[90:93]
	s_waitcnt lgkmcnt(1)
	v_mfma_f32_16x16x32_bf16 v[78:81], v[138:141], v[196:199], v[78:81]
	v_mfma_f32_16x16x32_bf16 v[74:77], v[148:151], v[196:199], v[74:77]
	v_mfma_f32_16x16x32_bf16 v[134:137], v[142:145], v[176:179], v[134:137]
	v_mfma_f32_16x16x32_bf16 v[122:125], v[152:155], v[176:179], v[122:125]
	v_mfma_f32_16x16x32_bf16 v[110:113], v[142:145], v[184:187], v[110:113]
	v_mfma_f32_16x16x32_bf16 v[106:109], v[152:155], v[184:187], v[106:109]
	v_mfma_f32_16x16x32_bf16 v[94:97], v[142:145], v[192:195], v[94:97]
	v_mfma_f32_16x16x32_bf16 v[90:93], v[152:155], v[192:195], v[90:93]
	s_waitcnt lgkmcnt(0)
	v_mfma_f32_16x16x32_bf16 v[78:81], v[142:145], v[200:203], v[78:81]
	v_mfma_f32_16x16x32_bf16 v[74:77], v[152:155], v[200:203], v[74:77]
	s_setprio 0
	s_setprio 1
	v_mfma_f32_16x16x32_bf16 v[118:121], v[156:159], v[172:175], v[118:121]
	v_mfma_f32_16x16x32_bf16 v[114:117], v[164:167], v[172:175], v[114:117]
	v_mfma_f32_16x16x32_bf16 v[102:105], v[156:159], v[180:183], v[102:105]
	v_mfma_f32_16x16x32_bf16 v[98:101], v[164:167], v[180:183], v[98:101]
	v_mfma_f32_16x16x32_bf16 v[86:89], v[156:159], v[188:191], v[86:89]
	v_mfma_f32_16x16x32_bf16 v[82:85], v[164:167], v[188:191], v[82:85]
	v_mfma_f32_16x16x32_bf16 v[70:73], v[156:159], v[196:199], v[70:73]
	v_mfma_f32_16x16x32_bf16 v[66:69], v[164:167], v[196:199], v[66:69]
	v_mfma_f32_16x16x32_bf16 v[118:121], v[160:163], v[176:179], v[118:121]
	v_mfma_f32_16x16x32_bf16 v[114:117], v[168:171], v[176:179], v[114:117]
	v_mfma_f32_16x16x32_bf16 v[102:105], v[160:163], v[184:187], v[102:105]
	v_mfma_f32_16x16x32_bf16 v[98:101], v[168:171], v[184:187], v[98:101]
	v_mfma_f32_16x16x32_bf16 v[86:89], v[160:163], v[192:195], v[86:89]
	v_mfma_f32_16x16x32_bf16 v[82:85], v[168:171], v[192:195], v[82:85]
	v_mfma_f32_16x16x32_bf16 v[70:73], v[160:163], v[200:203], v[70:73]
	v_mfma_f32_16x16x32_bf16 v[66:69], v[168:171], v[200:203], v[66:69]
	s_setprio 0
	s_barrier
	ds_read_b128 v[172:175], v133 offset:16384
	ds_read_b128 v[176:179], v133 offset:17408
	s_mov_b32 m0, s29
	s_nop 0
	buffer_load_dwordx4 v130, s[8:11], s58 offen lds
	ds_read_b128 v[180:183], v133 offset:18432
	ds_read_b128 v[184:187], v133 offset:19456
	s_add_i32 s59, s58, 0xb0000
	s_mov_b32 m0, s34
	s_nop 0
	buffer_load_dwordx4 v131, s[8:11], s58 offen lds
	ds_read_b128 v[188:191], v133 offset:20480
	ds_read_b128 v[192:195], v133 offset:21504
	s_nop 0
	s_mov_b32 m0, s35
	s_nop 0
	buffer_load_dwordx4 v130, s[8:11], s59 offen lds
	ds_read_b128 v[196:199], v133 offset:22528
	ds_read_b128 v[200:203], v133 offset:23552
	s_nop 0
	s_mov_b32 m0, s36
	s_nop 0
	buffer_load_dwordx4 v131, s[8:11], s59 offen lds
	s_nop 0
	s_mov_b32 m0, s28
	s_nop 0
	buffer_load_dwordx4 v130, s[12:15], s60 offen lds
	s_nop 0
	s_mov_b32 m0, s37
	s_nop 0
	buffer_load_dwordx4 v131, s[12:15], s60 offen lds
	s_waitcnt vmcnt(8)
	s_waitcnt lgkmcnt(0)
	s_barrier
	s_setprio 1
	s_waitcnt lgkmcnt(7)
	v_mfma_f32_16x16x32_bf16 v[62:65], v[138:141], v[172:175], v[62:65]
	v_mfma_f32_16x16x32_bf16 v[58:61], v[148:151], v[172:175], v[58:61]
	s_waitcnt lgkmcnt(5)
	v_mfma_f32_16x16x32_bf16 v[46:49], v[138:141], v[180:183], v[46:49]
	v_mfma_f32_16x16x32_bf16 v[42:45], v[148:151], v[180:183], v[42:45]
	s_waitcnt lgkmcnt(3)
	v_mfma_f32_16x16x32_bf16 v[30:33], v[138:141], v[188:191], v[30:33]
	v_mfma_f32_16x16x32_bf16 v[26:29], v[148:151], v[188:191], v[26:29]
	s_waitcnt lgkmcnt(1)
	v_mfma_f32_16x16x32_bf16 v[14:17], v[138:141], v[196:199], v[14:17]
	v_mfma_f32_16x16x32_bf16 v[10:13], v[148:151], v[196:199], v[10:13]
	v_mfma_f32_16x16x32_bf16 v[62:65], v[142:145], v[176:179], v[62:65]
	v_mfma_f32_16x16x32_bf16 v[58:61], v[152:155], v[176:179], v[58:61]
	v_mfma_f32_16x16x32_bf16 v[46:49], v[142:145], v[184:187], v[46:49]
	v_mfma_f32_16x16x32_bf16 v[42:45], v[152:155], v[184:187], v[42:45]
	v_mfma_f32_16x16x32_bf16 v[30:33], v[142:145], v[192:195], v[30:33]
	v_mfma_f32_16x16x32_bf16 v[26:29], v[152:155], v[192:195], v[26:29]
	s_waitcnt lgkmcnt(0)
	v_mfma_f32_16x16x32_bf16 v[14:17], v[142:145], v[200:203], v[14:17]
	v_mfma_f32_16x16x32_bf16 v[10:13], v[152:155], v[200:203], v[10:13]
	s_setprio 0
	s_setprio 1
	v_mfma_f32_16x16x32_bf16 v[54:57], v[156:159], v[172:175], v[54:57]
	v_mfma_f32_16x16x32_bf16 v[50:53], v[164:167], v[172:175], v[50:53]
	v_mfma_f32_16x16x32_bf16 v[38:41], v[156:159], v[180:183], v[38:41]
	v_mfma_f32_16x16x32_bf16 v[34:37], v[164:167], v[180:183], v[34:37]
	v_mfma_f32_16x16x32_bf16 v[22:25], v[156:159], v[188:191], v[22:25]
	v_mfma_f32_16x16x32_bf16 v[18:21], v[164:167], v[188:191], v[18:21]
	v_mfma_f32_16x16x32_bf16 v[6:9], v[156:159], v[196:199], v[6:9]
	v_mfma_f32_16x16x32_bf16 v[2:5], v[164:167], v[196:199], v[2:5]
	v_mfma_f32_16x16x32_bf16 v[54:57], v[160:163], v[176:179], v[54:57]
	v_mfma_f32_16x16x32_bf16 v[50:53], v[168:171], v[176:179], v[50:53]
	v_mfma_f32_16x16x32_bf16 v[38:41], v[160:163], v[184:187], v[38:41]
	v_mfma_f32_16x16x32_bf16 v[34:37], v[168:171], v[184:187], v[34:37]
	v_mfma_f32_16x16x32_bf16 v[22:25], v[160:163], v[192:195], v[22:25]
	v_mfma_f32_16x16x32_bf16 v[18:21], v[168:171], v[192:195], v[18:21]
	v_mfma_f32_16x16x32_bf16 v[6:9], v[160:163], v[200:203], v[6:9]
	v_mfma_f32_16x16x32_bf16 v[2:5], v[168:171], v[200:203], v[2:5]
	s_setprio 0
	s_barrier
	v_add_u32_e32 v147, 0x18000, v132
	ds_read_b128 v[138:141], v147
	ds_read_b128 v[142:145], v147 offset:1024
	ds_read_b128 v[148:151], v147 offset:2048
	ds_read_b128 v[152:155], v147 offset:3072
	v_add_u32_e32 v147, 0x1c000, v132
	ds_read_b128 v[156:159], v147
	ds_read_b128 v[160:163], v147 offset:1024
	ds_read_b128 v[164:167], v147 offset:2048
	ds_read_b128 v[168:171], v147 offset:3072
	ds_read_b128 v[172:175], v133 offset:32768
	ds_read_b128 v[176:179], v133 offset:33792
	ds_read_b128 v[180:183], v133 offset:34816
	ds_read_b128 v[184:187], v133 offset:35840
	ds_read_b128 v[188:191], v133 offset:36864
	ds_read_b128 v[192:195], v133 offset:37888
	ds_read_b128 v[196:199], v133 offset:38912
	ds_read_b128 v[200:203], v133 offset:39936
	s_add_i32 s59, s60, 0xb0000
	s_mov_b32 m0, s38
	s_nop 0
	buffer_load_dwordx4 v130, s[12:15], s59 offen lds
	s_nop 0
	s_mov_b32 m0, s39
	s_nop 0
	buffer_load_dwordx4 v131, s[12:15], s59 offen lds
	s_waitcnt vmcnt(8)
	s_waitcnt lgkmcnt(0)
	s_barrier
	s_setprio 1
	s_waitcnt lgkmcnt(7)
	v_mfma_f32_16x16x32_bf16 v[134:137], v[138:141], v[172:175], v[134:137]
	v_mfma_f32_16x16x32_bf16 v[122:125], v[148:151], v[172:175], v[122:125]
	s_waitcnt lgkmcnt(5)
	v_mfma_f32_16x16x32_bf16 v[110:113], v[138:141], v[180:183], v[110:113]
	v_mfma_f32_16x16x32_bf16 v[106:109], v[148:151], v[180:183], v[106:109]
	s_waitcnt lgkmcnt(3)
	v_mfma_f32_16x16x32_bf16 v[94:97], v[138:141], v[188:191], v[94:97]
	v_mfma_f32_16x16x32_bf16 v[90:93], v[148:151], v[188:191], v[90:93]
	s_waitcnt lgkmcnt(1)
	v_mfma_f32_16x16x32_bf16 v[78:81], v[138:141], v[196:199], v[78:81]
	v_mfma_f32_16x16x32_bf16 v[74:77], v[148:151], v[196:199], v[74:77]
	v_mfma_f32_16x16x32_bf16 v[134:137], v[142:145], v[176:179], v[134:137]
	v_mfma_f32_16x16x32_bf16 v[122:125], v[152:155], v[176:179], v[122:125]
	v_mfma_f32_16x16x32_bf16 v[110:113], v[142:145], v[184:187], v[110:113]
	v_mfma_f32_16x16x32_bf16 v[106:109], v[152:155], v[184:187], v[106:109]
	v_mfma_f32_16x16x32_bf16 v[94:97], v[142:145], v[192:195], v[94:97]
	v_mfma_f32_16x16x32_bf16 v[90:93], v[152:155], v[192:195], v[90:93]
	s_waitcnt lgkmcnt(0)
	v_mfma_f32_16x16x32_bf16 v[78:81], v[142:145], v[200:203], v[78:81]
	v_mfma_f32_16x16x32_bf16 v[74:77], v[152:155], v[200:203], v[74:77]
	s_setprio 0
	s_setprio 1
	v_mfma_f32_16x16x32_bf16 v[118:121], v[156:159], v[172:175], v[118:121]
	v_mfma_f32_16x16x32_bf16 v[114:117], v[164:167], v[172:175], v[114:117]
	v_mfma_f32_16x16x32_bf16 v[102:105], v[156:159], v[180:183], v[102:105]
	v_mfma_f32_16x16x32_bf16 v[98:101], v[164:167], v[180:183], v[98:101]
	v_mfma_f32_16x16x32_bf16 v[86:89], v[156:159], v[188:191], v[86:89]
	v_mfma_f32_16x16x32_bf16 v[82:85], v[164:167], v[188:191], v[82:85]
	v_mfma_f32_16x16x32_bf16 v[70:73], v[156:159], v[196:199], v[70:73]
	v_mfma_f32_16x16x32_bf16 v[66:69], v[164:167], v[196:199], v[66:69]
	v_mfma_f32_16x16x32_bf16 v[118:121], v[160:163], v[176:179], v[118:121]
	v_mfma_f32_16x16x32_bf16 v[114:117], v[168:171], v[176:179], v[114:117]
	v_mfma_f32_16x16x32_bf16 v[102:105], v[160:163], v[184:187], v[102:105]
	v_mfma_f32_16x16x32_bf16 v[98:101], v[168:171], v[184:187], v[98:101]
	v_mfma_f32_16x16x32_bf16 v[86:89], v[160:163], v[192:195], v[86:89]
	v_mfma_f32_16x16x32_bf16 v[82:85], v[168:171], v[192:195], v[82:85]
	v_mfma_f32_16x16x32_bf16 v[70:73], v[160:163], v[200:203], v[70:73]
	v_mfma_f32_16x16x32_bf16 v[66:69], v[168:171], v[200:203], v[66:69]
	s_setprio 0
	s_barrier
	ds_read_b128 v[172:175], v133 offset:49152
	ds_read_b128 v[176:179], v133 offset:50176
	s_add_i32 s59, s58, 0x80
	s_mov_b32 m0, s40
	s_nop 0
	buffer_load_dwordx4 v130, s[8:11], s59 offen lds
	ds_read_b128 v[180:183], v133 offset:51200
	ds_read_b128 v[184:187], v133 offset:52224
	s_add_i32 s58, s58, 0xb0080
	s_mov_b32 m0, s41
	s_nop 0
	buffer_load_dwordx4 v131, s[8:11], s59 offen lds
	ds_read_b128 v[188:191], v133 offset:53248
	ds_read_b128 v[192:195], v133 offset:54272
	s_nop 0
	s_mov_b32 m0, s44
	s_nop 0
	buffer_load_dwordx4 v130, s[8:11], s58 offen lds
	ds_read_b128 v[196:199], v133 offset:55296
	ds_read_b128 v[200:203], v133 offset:56320
	s_nop 0
	s_mov_b32 m0, s45
	s_nop 0
	buffer_load_dwordx4 v131, s[8:11], s58 offen lds
	s_nop 0
	s_mov_b32 m0, s42
	s_nop 0
	buffer_load_dwordx4 v130, s[12:15], s55 offen lds
	s_nop 0
	s_mov_b32 m0, s43
	s_nop 0
	buffer_load_dwordx4 v131, s[12:15], s55 offen lds
	s_waitcnt vmcnt(8)
	s_waitcnt lgkmcnt(0)
	s_barrier
	s_setprio 1
	s_waitcnt lgkmcnt(7)
	v_mfma_f32_16x16x32_bf16 v[62:65], v[138:141], v[172:175], v[62:65]
	v_mfma_f32_16x16x32_bf16 v[58:61], v[148:151], v[172:175], v[58:61]
	s_waitcnt lgkmcnt(5)
	v_mfma_f32_16x16x32_bf16 v[46:49], v[138:141], v[180:183], v[46:49]
	v_mfma_f32_16x16x32_bf16 v[42:45], v[148:151], v[180:183], v[42:45]
	s_waitcnt lgkmcnt(3)
	v_mfma_f32_16x16x32_bf16 v[30:33], v[138:141], v[188:191], v[30:33]
	v_mfma_f32_16x16x32_bf16 v[26:29], v[148:151], v[188:191], v[26:29]
	s_waitcnt lgkmcnt(1)
	v_mfma_f32_16x16x32_bf16 v[14:17], v[138:141], v[196:199], v[14:17]
	v_mfma_f32_16x16x32_bf16 v[10:13], v[148:151], v[196:199], v[10:13]
	v_mfma_f32_16x16x32_bf16 v[62:65], v[142:145], v[176:179], v[62:65]
	v_mfma_f32_16x16x32_bf16 v[58:61], v[152:155], v[176:179], v[58:61]
	v_mfma_f32_16x16x32_bf16 v[46:49], v[142:145], v[184:187], v[46:49]
	v_mfma_f32_16x16x32_bf16 v[42:45], v[152:155], v[184:187], v[42:45]
	v_mfma_f32_16x16x32_bf16 v[30:33], v[142:145], v[192:195], v[30:33]
	v_mfma_f32_16x16x32_bf16 v[26:29], v[152:155], v[192:195], v[26:29]
	s_waitcnt lgkmcnt(0)
	v_mfma_f32_16x16x32_bf16 v[14:17], v[142:145], v[200:203], v[14:17]
	v_mfma_f32_16x16x32_bf16 v[10:13], v[152:155], v[200:203], v[10:13]
	s_setprio 0
	s_setprio 1
	v_mfma_f32_16x16x32_bf16 v[54:57], v[156:159], v[172:175], v[54:57]
	v_mfma_f32_16x16x32_bf16 v[50:53], v[164:167], v[172:175], v[50:53]
	v_mfma_f32_16x16x32_bf16 v[38:41], v[156:159], v[180:183], v[38:41]
	v_mfma_f32_16x16x32_bf16 v[34:37], v[164:167], v[180:183], v[34:37]
	v_mfma_f32_16x16x32_bf16 v[22:25], v[156:159], v[188:191], v[22:25]
	v_mfma_f32_16x16x32_bf16 v[18:21], v[164:167], v[188:191], v[18:21]
	v_mfma_f32_16x16x32_bf16 v[6:9], v[156:159], v[196:199], v[6:9]
	v_mfma_f32_16x16x32_bf16 v[2:5], v[164:167], v[196:199], v[2:5]
	v_mfma_f32_16x16x32_bf16 v[54:57], v[160:163], v[176:179], v[54:57]
	v_mfma_f32_16x16x32_bf16 v[50:53], v[168:171], v[176:179], v[50:53]
	v_mfma_f32_16x16x32_bf16 v[38:41], v[160:163], v[184:187], v[38:41]
	v_mfma_f32_16x16x32_bf16 v[34:37], v[168:171], v[184:187], v[34:37]
	v_mfma_f32_16x16x32_bf16 v[22:25], v[160:163], v[192:195], v[22:25]
	v_mfma_f32_16x16x32_bf16 v[18:21], v[168:171], v[192:195], v[18:21]
	v_mfma_f32_16x16x32_bf16 v[6:9], v[160:163], v[200:203], v[6:9]
	v_mfma_f32_16x16x32_bf16 v[2:5], v[168:171], v[200:203], v[2:5]
	s_setprio 0
	s_barrier
	s_add_i32 s0, s0, 2
	s_addk_i32 s1, 0x100
	s_cmp_gt_u32 s0, 41
	s_cbranch_scc0 .LBB0_467
	s_andn2_b64 vcc, exec, s[6:7]
	s_cbranch_vccnz .LBB0_455
	v_mov_b32_e32 v2, 0
	s_mov_b32 s18, s50
	s_mov_b32 s31, s51
	s_mov_b32 s33, s54
	s_mov_b32 s3, s53
	s_mov_b32 s49, s52
	v_mov_b32_e32 v3, v2
	v_mov_b32_e32 v4, v2
	v_mov_b32_e32 v5, v2
	v_mov_b32_e32 v6, v2
	v_mov_b32_e32 v7, v2
	v_mov_b32_e32 v8, v2
	v_mov_b32_e32 v9, v2
	v_mov_b32_e32 v18, v2
	v_mov_b32_e32 v19, v2
	v_mov_b32_e32 v20, v2
	v_mov_b32_e32 v21, v2
	v_mov_b32_e32 v22, v2
	v_mov_b32_e32 v23, v2
	v_mov_b32_e32 v24, v2
	v_mov_b32_e32 v25, v2
	v_mov_b32_e32 v34, v2
	v_mov_b32_e32 v35, v2
	v_mov_b32_e32 v36, v2
	v_mov_b32_e32 v37, v2
	v_mov_b32_e32 v38, v2
	v_mov_b32_e32 v39, v2
	v_mov_b32_e32 v40, v2
	v_mov_b32_e32 v41, v2
	v_mov_b32_e32 v50, v2
	v_mov_b32_e32 v51, v2
	v_mov_b32_e32 v52, v2
	v_mov_b32_e32 v53, v2
	v_mov_b32_e32 v54, v2
	v_mov_b32_e32 v55, v2
	v_mov_b32_e32 v56, v2
	v_mov_b32_e32 v57, v2
	v_mov_b32_e32 v10, v2
	v_mov_b32_e32 v11, v2
	v_mov_b32_e32 v12, v2
	v_mov_b32_e32 v13, v2
	v_mov_b32_e32 v14, v2
	v_mov_b32_e32 v15, v2
	v_mov_b32_e32 v16, v2
	v_mov_b32_e32 v17, v2
	v_mov_b32_e32 v26, v2
	v_mov_b32_e32 v27, v2
	v_mov_b32_e32 v28, v2
	v_mov_b32_e32 v29, v2
	v_mov_b32_e32 v30, v2
	v_mov_b32_e32 v31, v2
	v_mov_b32_e32 v32, v2
	v_mov_b32_e32 v33, v2
	v_mov_b32_e32 v42, v2
	v_mov_b32_e32 v43, v2
	v_mov_b32_e32 v44, v2
	v_mov_b32_e32 v45, v2
	v_mov_b32_e32 v46, v2
	v_mov_b32_e32 v47, v2
	v_mov_b32_e32 v48, v2
	v_mov_b32_e32 v49, v2
	v_mov_b32_e32 v58, v2
	v_mov_b32_e32 v59, v2
	v_mov_b32_e32 v60, v2
	v_mov_b32_e32 v61, v2
	v_mov_b32_e32 v62, v2
	v_mov_b32_e32 v63, v2
	v_mov_b32_e32 v64, v2
	v_mov_b32_e32 v65, v2
	v_mov_b32_e32 v66, v2
	v_mov_b32_e32 v67, v2
	v_mov_b32_e32 v68, v2
	v_mov_b32_e32 v69, v2
	v_mov_b32_e32 v70, v2
	v_mov_b32_e32 v71, v2
	v_mov_b32_e32 v72, v2
	v_mov_b32_e32 v73, v2
	v_mov_b32_e32 v82, v2
	v_mov_b32_e32 v83, v2
	v_mov_b32_e32 v84, v2
	v_mov_b32_e32 v85, v2
	v_mov_b32_e32 v86, v2
	v_mov_b32_e32 v87, v2
	v_mov_b32_e32 v88, v2
	v_mov_b32_e32 v89, v2
	v_mov_b32_e32 v98, v2
	v_mov_b32_e32 v99, v2
	v_mov_b32_e32 v100, v2
	v_mov_b32_e32 v101, v2
	v_mov_b32_e32 v102, v2
	v_mov_b32_e32 v103, v2
	v_mov_b32_e32 v104, v2
	v_mov_b32_e32 v105, v2
	v_mov_b32_e32 v114, v2
	v_mov_b32_e32 v115, v2
	v_mov_b32_e32 v116, v2
	v_mov_b32_e32 v117, v2
	v_mov_b32_e32 v118, v2
	v_mov_b32_e32 v119, v2
	v_mov_b32_e32 v120, v2
	v_mov_b32_e32 v121, v2
	v_mov_b32_e32 v74, v2
	v_mov_b32_e32 v75, v2
	v_mov_b32_e32 v76, v2
	v_mov_b32_e32 v77, v2
	v_mov_b32_e32 v78, v2
	v_mov_b32_e32 v79, v2
	v_mov_b32_e32 v80, v2
	v_mov_b32_e32 v81, v2
	v_mov_b32_e32 v90, v2
	v_mov_b32_e32 v91, v2
	v_mov_b32_e32 v92, v2
	v_mov_b32_e32 v93, v2
	v_mov_b32_e32 v94, v2
	v_mov_b32_e32 v95, v2
	v_mov_b32_e32 v96, v2
	v_mov_b32_e32 v97, v2
	v_mov_b32_e32 v106, v2
	v_mov_b32_e32 v107, v2
	v_mov_b32_e32 v108, v2
	v_mov_b32_e32 v109, v2
	v_mov_b32_e32 v110, v2
	v_mov_b32_e32 v111, v2
	v_mov_b32_e32 v112, v2
	v_mov_b32_e32 v113, v2
	v_mov_b32_e32 v122, v2
	v_mov_b32_e32 v123, v2
	v_mov_b32_e32 v124, v2
	v_mov_b32_e32 v125, v2
	v_mov_b32_e32 v134, v2
	v_mov_b32_e32 v135, v2
	v_mov_b32_e32 v136, v2
	v_mov_b32_e32 v137, v2
	s_branch .LBB0_455

.LBB0_619:
	ds_read_b128 v[38:41], v210
	ds_read_b128 v[42:45], v210 offset:1024
	ds_read_b128 v[46:49], v210 offset:2048
	ds_read_b128 v[58:61], v210 offset:3072
	ds_read_b128 v[142:145], v211
	ds_read_b128 v[146:149], v211 offset:1024
	ds_read_b128 v[150:153], v211 offset:2048
	ds_read_b128 v[154:157], v211 offset:3072
	s_add_i32 s6, s1, 0xfffe0080
	s_cmp_eq_u32 s3, 4
	s_cselect_b32 s8, s75, s6
	s_cselect_b32 s7, s0, s2
	s_add_i32 s6, s8, 0x80
	ds_read_b128 v[166:169], v212
	ds_read_b128 v[170:173], v212 offset:1024
	ds_read_b128 v[174:177], v212 offset:2048
	ds_read_b128 v[178:181], v212 offset:3072
	ds_read_b128 v[190:193], v212 offset:4096
	ds_read_b128 v[194:197], v212 offset:5120
	ds_read_b128 v[198:201], v212 offset:6144
	ds_read_b128 v[216:219], v212 offset:7168
	s_mov_b32 m0, s68
	s_nop 0
	buffer_load_dwordx4 v206, s[16:19], s1 offen lds
	s_nop 0
	s_mov_b32 m0, s69
	s_nop 0
	buffer_load_dwordx4 v207, s[16:19], s1 offen lds
	s_waitcnt vmcnt(8)
	s_waitcnt lgkmcnt(0)
	s_barrier
	s_setprio 1
	s_waitcnt lgkmcnt(7)
	v_mfma_i32_16x16x64_i8 v[162:165], v[38:41], v[166:169], v[162:165]
	v_mfma_i32_16x16x64_i8 v[158:161], v[46:49], v[166:169], v[158:161]
	s_waitcnt lgkmcnt(5)
	v_mfma_i32_16x16x64_i8 v[130:133], v[38:41], v[174:177], v[130:133]
	v_mfma_i32_16x16x64_i8 v[126:129], v[46:49], v[174:177], v[126:129]
	s_waitcnt lgkmcnt(3)
	v_mfma_i32_16x16x64_i8 v[114:117], v[38:41], v[190:193], v[114:117]
	v_mfma_i32_16x16x64_i8 v[110:113], v[46:49], v[190:193], v[110:113]
	s_waitcnt lgkmcnt(1)
	v_mfma_i32_16x16x64_i8 v[98:101], v[38:41], v[198:201], v[98:101]
	v_mfma_i32_16x16x64_i8 v[94:97], v[46:49], v[198:201], v[94:97]
	v_mfma_i32_16x16x64_i8 v[162:165], v[42:45], v[170:173], v[162:165]
	v_mfma_i32_16x16x64_i8 v[158:161], v[58:61], v[170:173], v[158:161]
	v_mfma_i32_16x16x64_i8 v[130:133], v[42:45], v[178:181], v[130:133]
	v_mfma_i32_16x16x64_i8 v[126:129], v[58:61], v[178:181], v[126:129]
	v_mfma_i32_16x16x64_i8 v[114:117], v[42:45], v[194:197], v[114:117]
	v_mfma_i32_16x16x64_i8 v[110:113], v[58:61], v[194:197], v[110:113]
	s_waitcnt lgkmcnt(0)
	v_mfma_i32_16x16x64_i8 v[98:101], v[42:45], v[216:219], v[98:101]
	v_mfma_i32_16x16x64_i8 v[94:97], v[58:61], v[216:219], v[94:97]
	s_setprio 0
	s_setprio 1
	v_mfma_i32_16x16x64_i8 v[138:141], v[142:145], v[166:169], v[138:141]
	v_mfma_i32_16x16x64_i8 v[134:137], v[150:153], v[166:169], v[134:137]
	v_mfma_i32_16x16x64_i8 v[122:125], v[142:145], v[174:177], v[122:125]
	v_mfma_i32_16x16x64_i8 v[118:121], v[150:153], v[174:177], v[118:121]
	v_mfma_i32_16x16x64_i8 v[106:109], v[142:145], v[190:193], v[106:109]
	v_mfma_i32_16x16x64_i8 v[102:105], v[150:153], v[190:193], v[102:105]
	v_mfma_i32_16x16x64_i8 v[90:93], v[142:145], v[198:201], v[90:93]
	v_mfma_i32_16x16x64_i8 v[86:89], v[150:153], v[198:201], v[86:89]
	v_mfma_i32_16x16x64_i8 v[138:141], v[146:149], v[170:173], v[138:141]
	v_mfma_i32_16x16x64_i8 v[134:137], v[154:157], v[170:173], v[134:137]
	v_mfma_i32_16x16x64_i8 v[122:125], v[146:149], v[178:181], v[122:125]
	v_mfma_i32_16x16x64_i8 v[118:121], v[154:157], v[178:181], v[118:121]
	v_mfma_i32_16x16x64_i8 v[106:109], v[146:149], v[194:197], v[106:109]
	v_mfma_i32_16x16x64_i8 v[102:105], v[154:157], v[194:197], v[102:105]
	v_mfma_i32_16x16x64_i8 v[90:93], v[146:149], v[216:219], v[90:93]
	v_mfma_i32_16x16x64_i8 v[86:89], v[154:157], v[216:219], v[86:89]
	s_setprio 0
	s_barrier
	ds_read_b128 v[166:169], v212 offset:16384
	ds_read_b128 v[170:173], v212 offset:17408
	s_mov_b32 m0, s48
	s_nop 0
	buffer_load_dwordx4 v204, s[12:15], s7 offen lds
	ds_read_b128 v[174:177], v212 offset:18432
	ds_read_b128 v[178:181], v212 offset:19456
	s_add_i32 s9, s7, 0x20000
	s_mov_b32 m0, s49
	s_nop 0
	buffer_load_dwordx4 v205, s[12:15], s7 offen lds
	ds_read_b128 v[190:193], v212 offset:20480
	ds_read_b128 v[194:197], v212 offset:21504
	s_nop 0
	s_mov_b32 m0, s50
	s_nop 0
	buffer_load_dwordx4 v204, s[12:15], s9 offen lds
	ds_read_b128 v[198:201], v212 offset:22528
	ds_read_b128 v[216:219], v212 offset:23552
	s_nop 0
	s_mov_b32 m0, s51
	s_nop 0
	buffer_load_dwordx4 v205, s[12:15], s9 offen lds
	s_nop 0
	s_mov_b32 m0, s47
	s_nop 0
	buffer_load_dwordx4 v206, s[16:19], s8 offen lds
	s_nop 0
	s_mov_b32 m0, s52
	s_nop 0
	buffer_load_dwordx4 v207, s[16:19], s8 offen lds
	s_waitcnt vmcnt(8)
	s_waitcnt lgkmcnt(0)
	s_barrier
	s_setprio 1
	s_waitcnt lgkmcnt(7)
	v_mfma_i32_16x16x64_i8 v[82:85], v[38:41], v[166:169], v[82:85]
	v_mfma_i32_16x16x64_i8 v[78:81], v[46:49], v[166:169], v[78:81]
	s_waitcnt lgkmcnt(5)
	v_mfma_i32_16x16x64_i8 v[66:69], v[38:41], v[174:177], v[66:69]
	v_mfma_i32_16x16x64_i8 v[62:65], v[46:49], v[174:177], v[62:65]
	s_waitcnt lgkmcnt(3)
	v_mfma_i32_16x16x64_i8 v[34:37], v[38:41], v[190:193], v[34:37]
	v_mfma_i32_16x16x64_i8 v[30:33], v[46:49], v[190:193], v[30:33]
	s_waitcnt lgkmcnt(1)
	v_mfma_i32_16x16x64_i8 v[18:21], v[38:41], v[198:201], v[18:21]
	v_mfma_i32_16x16x64_i8 v[14:17], v[46:49], v[198:201], v[14:17]
	v_mfma_i32_16x16x64_i8 v[82:85], v[42:45], v[170:173], v[82:85]
	v_mfma_i32_16x16x64_i8 v[78:81], v[58:61], v[170:173], v[78:81]
	v_mfma_i32_16x16x64_i8 v[66:69], v[42:45], v[178:181], v[66:69]
	v_mfma_i32_16x16x64_i8 v[62:65], v[58:61], v[178:181], v[62:65]
	v_mfma_i32_16x16x64_i8 v[34:37], v[42:45], v[194:197], v[34:37]
	v_mfma_i32_16x16x64_i8 v[30:33], v[58:61], v[194:197], v[30:33]
	s_waitcnt lgkmcnt(0)
	v_mfma_i32_16x16x64_i8 v[18:21], v[42:45], v[216:219], v[18:21]
	v_mfma_i32_16x16x64_i8 v[14:17], v[58:61], v[216:219], v[14:17]
	s_setprio 0
	s_setprio 1
	v_mfma_i32_16x16x64_i8 v[50:53], v[150:153], v[174:177], v[50:53]
	v_mfma_i32_16x16x64_i8 v[26:29], v[142:145], v[190:193], v[26:29]
	v_mfma_i32_16x16x64_i8 v[22:25], v[150:153], v[190:193], v[22:25]
	v_mfma_i32_16x16x64_i8 v[10:13], v[142:145], v[198:201], v[10:13]
	v_mfma_i32_16x16x64_i8 v[4:7], v[150:153], v[198:201], v[6:9]
	v_mfma_i32_16x16x64_i8 v[38:41], v[142:145], v[166:169], v[74:77]
	v_mfma_i32_16x16x64_i8 v[42:45], v[150:153], v[166:169], v[70:73]
	v_mfma_i32_16x16x64_i8 v[46:49], v[142:145], v[174:177], v[54:57]
	v_mfma_i32_16x16x64_i8 v[50:53], v[154:157], v[178:181], v[50:53]
	v_mfma_i32_16x16x64_i8 v[26:29], v[146:149], v[194:197], v[26:29]
	v_mfma_i32_16x16x64_i8 v[22:25], v[154:157], v[194:197], v[22:25]
	v_mfma_i32_16x16x64_i8 v[10:13], v[146:149], v[216:219], v[10:13]
	v_mfma_i32_16x16x64_i8 v[4:7], v[154:157], v[216:219], v[4:7]
	v_mfma_i32_16x16x64_i8 v[38:41], v[146:149], v[170:173], v[38:41]
	v_mfma_i32_16x16x64_i8 v[42:45], v[154:157], v[170:173], v[42:45]
	v_mfma_i32_16x16x64_i8 v[46:49], v[146:149], v[178:181], v[46:49]
	s_setprio 0
	s_barrier
	ds_read_b128 v[54:57], v213
	ds_read_b128 v[58:61], v213 offset:1024
	ds_read_b128 v[70:73], v213 offset:2048
	ds_read_b128 v[74:77], v213 offset:3072
	ds_read_b128 v[142:145], v214
	ds_read_b128 v[146:149], v214 offset:1024
	ds_read_b128 v[150:153], v214 offset:2048
	ds_read_b128 v[154:157], v214 offset:3072
	ds_read_b128 v[166:169], v212 offset:32768
	ds_read_b128 v[170:173], v212 offset:33792
	ds_read_b128 v[174:177], v212 offset:34816
	ds_read_b128 v[178:181], v212 offset:35840
	ds_read_b128 v[190:193], v212 offset:36864
	ds_read_b128 v[194:197], v212 offset:37888
	ds_read_b128 v[198:201], v212 offset:38912
	ds_read_b128 v[216:219], v212 offset:39936
	s_add_i32 s8, s8, 0x20000
	s_mov_b32 m0, s53
	s_nop 0
	buffer_load_dwordx4 v206, s[16:19], s8 offen lds
	s_nop 0
	s_mov_b32 m0, s54
	s_nop 0
	buffer_load_dwordx4 v207, s[16:19], s8 offen lds
	s_waitcnt vmcnt(8)
	s_waitcnt lgkmcnt(0)
	s_barrier
	s_setprio 1
	s_waitcnt lgkmcnt(7)
	v_mfma_i32_16x16x64_i8 v[162:165], v[54:57], v[166:169], v[162:165]
	v_mfma_i32_16x16x64_i8 v[158:161], v[70:73], v[166:169], v[158:161]
	s_waitcnt lgkmcnt(5)
	v_mfma_i32_16x16x64_i8 v[130:133], v[54:57], v[174:177], v[130:133]
	v_mfma_i32_16x16x64_i8 v[126:129], v[70:73], v[174:177], v[126:129]
	s_waitcnt lgkmcnt(3)
	v_mfma_i32_16x16x64_i8 v[114:117], v[54:57], v[190:193], v[114:117]
	v_mfma_i32_16x16x64_i8 v[110:113], v[70:73], v[190:193], v[110:113]
	s_waitcnt lgkmcnt(1)
	v_mfma_i32_16x16x64_i8 v[98:101], v[54:57], v[198:201], v[98:101]
	v_mfma_i32_16x16x64_i8 v[94:97], v[70:73], v[198:201], v[94:97]
	v_mfma_i32_16x16x64_i8 v[162:165], v[58:61], v[170:173], v[162:165]
	v_mfma_i32_16x16x64_i8 v[158:161], v[74:77], v[170:173], v[158:161]
	v_mfma_i32_16x16x64_i8 v[130:133], v[58:61], v[178:181], v[130:133]
	v_mfma_i32_16x16x64_i8 v[126:129], v[74:77], v[178:181], v[126:129]
	v_mfma_i32_16x16x64_i8 v[114:117], v[58:61], v[194:197], v[114:117]
	v_mfma_i32_16x16x64_i8 v[110:113], v[74:77], v[194:197], v[110:113]
	s_waitcnt lgkmcnt(0)
	v_mfma_i32_16x16x64_i8 v[98:101], v[58:61], v[216:219], v[98:101]
	v_mfma_i32_16x16x64_i8 v[94:97], v[74:77], v[216:219], v[94:97]
	s_setprio 0
	s_setprio 1
	v_mfma_i32_16x16x64_i8 v[138:141], v[142:145], v[166:169], v[138:141]
	v_mfma_i32_16x16x64_i8 v[134:137], v[150:153], v[166:169], v[134:137]
	v_mfma_i32_16x16x64_i8 v[122:125], v[142:145], v[174:177], v[122:125]
	v_mfma_i32_16x16x64_i8 v[118:121], v[150:153], v[174:177], v[118:121]
	v_mfma_i32_16x16x64_i8 v[106:109], v[142:145], v[190:193], v[106:109]
	v_mfma_i32_16x16x64_i8 v[102:105], v[150:153], v[190:193], v[102:105]
	v_mfma_i32_16x16x64_i8 v[90:93], v[142:145], v[198:201], v[90:93]
	v_mfma_i32_16x16x64_i8 v[86:89], v[150:153], v[198:201], v[86:89]
	v_mfma_i32_16x16x64_i8 v[138:141], v[146:149], v[170:173], v[138:141]
	v_mfma_i32_16x16x64_i8 v[134:137], v[154:157], v[170:173], v[134:137]
	v_mfma_i32_16x16x64_i8 v[122:125], v[146:149], v[178:181], v[122:125]
	v_mfma_i32_16x16x64_i8 v[118:121], v[154:157], v[178:181], v[118:121]
	v_mfma_i32_16x16x64_i8 v[106:109], v[146:149], v[194:197], v[106:109]
	v_mfma_i32_16x16x64_i8 v[102:105], v[154:157], v[194:197], v[102:105]
	v_mfma_i32_16x16x64_i8 v[90:93], v[146:149], v[216:219], v[90:93]
	v_mfma_i32_16x16x64_i8 v[86:89], v[154:157], v[216:219], v[86:89]
	s_setprio 0
	s_barrier
	ds_read_b128 v[166:169], v212 offset:49152
	ds_read_b128 v[170:173], v212 offset:50176
	s_or_b32 s8, s7, 0x80
	s_mov_b32 m0, s62
	s_nop 0
	buffer_load_dwordx4 v204, s[12:15], s8 offen lds
	ds_read_b128 v[174:177], v212 offset:51200
	ds_read_b128 v[178:181], v212 offset:52224
	s_add_i32 s7, s7, 0x20080
	s_mov_b32 m0, s63
	s_nop 0
	buffer_load_dwordx4 v205, s[12:15], s8 offen lds
	ds_read_b128 v[190:193], v212 offset:53248
	ds_read_b128 v[194:197], v212 offset:54272
	s_nop 0
	s_mov_b32 m0, s66
	s_nop 0
	buffer_load_dwordx4 v204, s[12:15], s7 offen lds
	ds_read_b128 v[198:201], v212 offset:55296
	ds_read_b128 v[216:219], v212 offset:56320
	s_nop 0
	s_mov_b32 m0, s67
	s_nop 0
	buffer_load_dwordx4 v205, s[12:15], s7 offen lds
	s_nop 0
	s_mov_b32 m0, s64
	s_nop 0
	buffer_load_dwordx4 v206, s[16:19], s6 offen lds
	s_nop 0
	s_mov_b32 m0, s65
	s_nop 0
	buffer_load_dwordx4 v207, s[16:19], s6 offen lds
	s_waitcnt vmcnt(8)
	s_waitcnt lgkmcnt(0)
	s_barrier
	s_setprio 1
	s_waitcnt lgkmcnt(7)
	v_mfma_i32_16x16x64_i8 v[82:85], v[54:57], v[166:169], v[82:85]
	v_mfma_i32_16x16x64_i8 v[78:81], v[70:73], v[166:169], v[78:81]
	s_waitcnt lgkmcnt(5)
	v_mfma_i32_16x16x64_i8 v[66:69], v[54:57], v[174:177], v[66:69]
	v_mfma_i32_16x16x64_i8 v[62:65], v[70:73], v[174:177], v[62:65]
	s_waitcnt lgkmcnt(3)
	v_mfma_i32_16x16x64_i8 v[34:37], v[54:57], v[190:193], v[34:37]
	v_mfma_i32_16x16x64_i8 v[30:33], v[70:73], v[190:193], v[30:33]
	s_waitcnt lgkmcnt(1)
	v_mfma_i32_16x16x64_i8 v[18:21], v[54:57], v[198:201], v[18:21]
	v_mfma_i32_16x16x64_i8 v[14:17], v[70:73], v[198:201], v[14:17]
	v_mfma_i32_16x16x64_i8 v[82:85], v[58:61], v[170:173], v[82:85]
	v_mfma_i32_16x16x64_i8 v[78:81], v[74:77], v[170:173], v[78:81]
	v_mfma_i32_16x16x64_i8 v[66:69], v[58:61], v[178:181], v[66:69]
	v_mfma_i32_16x16x64_i8 v[62:65], v[74:77], v[178:181], v[62:65]
	v_mfma_i32_16x16x64_i8 v[34:37], v[58:61], v[194:197], v[34:37]
	v_mfma_i32_16x16x64_i8 v[30:33], v[74:77], v[194:197], v[30:33]
	s_waitcnt lgkmcnt(0)
	v_mfma_i32_16x16x64_i8 v[18:21], v[58:61], v[216:219], v[18:21]
	v_mfma_i32_16x16x64_i8 v[14:17], v[74:77], v[216:219], v[14:17]
	s_setprio 0
	s_setprio 1
	v_mfma_i32_16x16x64_i8 v[38:41], v[142:145], v[166:169], v[38:41]
	v_mfma_i32_16x16x64_i8 v[74:77], v[146:149], v[170:173], v[38:41]
	v_mfma_i32_16x16x64_i8 v[38:41], v[150:153], v[166:169], v[42:45]
	v_mfma_i32_16x16x64_i8 v[70:73], v[154:157], v[170:173], v[38:41]
	v_mfma_i32_16x16x64_i8 v[38:41], v[142:145], v[174:177], v[46:49]
	v_mfma_i32_16x16x64_i8 v[54:57], v[146:149], v[178:181], v[38:41]
	v_mfma_i32_16x16x64_i8 v[38:41], v[150:153], v[174:177], v[50:53]
	v_mfma_i32_16x16x64_i8 v[26:29], v[142:145], v[190:193], v[26:29]
	v_mfma_i32_16x16x64_i8 v[22:25], v[150:153], v[190:193], v[22:25]
	v_mfma_i32_16x16x64_i8 v[8:11], v[142:145], v[198:201], v[10:13]
	v_mfma_i32_16x16x64_i8 v[4:7], v[150:153], v[198:201], v[4:7]
	v_mfma_i32_16x16x64_i8 v[50:53], v[154:157], v[178:181], v[38:41]
	v_mfma_i32_16x16x64_i8 v[26:29], v[146:149], v[194:197], v[26:29]
	v_mfma_i32_16x16x64_i8 v[22:25], v[154:157], v[194:197], v[22:25]
	v_mfma_i32_16x16x64_i8 v[10:13], v[146:149], v[216:219], v[8:11]
	v_mfma_i32_16x16x64_i8 v[6:9], v[154:157], v[216:219], v[4:7]
	s_setprio 0
	s_barrier
	s_add_i32 s3, s3, 2
	s_addk_i32 s1, 0x100
	s_addk_i32 s2, 0x100
	s_cmp_gt_u32 s3, 5
	s_cbranch_scc0 .LBB0_619
	s_and_b64 vcc, exec, s[34:35]
	s_cbranch_vccz .LBB0_622
	s_barrier

.LBB0_943:
	v_add_u32_e32 v150, 0x10000, v8
	v_add_u32_e32 v166, 0x14000, v8
	ds_read_b128 v[10:13], v150
	ds_read_b128 v[14:17], v150 offset:1024
	ds_read_b128 v[146:149], v150 offset:2048
	ds_read_b128 v[150:153], v150 offset:3072
	ds_read_b128 v[154:157], v166
	ds_read_b128 v[158:161], v166 offset:1024
	ds_read_b128 v[162:165], v166 offset:2048
	ds_read_b128 v[166:169], v166 offset:3072
	s_add_i32 s61, s37, s58
	s_add_i32 s60, s33, s58
	s_add_i32 s59, s61, 0x400
	s_addk_i32 s60, 0x400
	s_cmp_eq_u32 s58, 0
	s_cselect_b32 s62, s53, s59
	s_cselect_b32 s60, s54, s60
	s_or_b32 s59, s62, 0x80
	ds_read_b128 v[170:173], v9
	ds_read_b128 v[174:177], v9 offset:1024
	ds_read_b128 v[178:181], v9 offset:2048
	ds_read_b128 v[182:185], v9 offset:3072
	ds_read_b128 v[186:189], v9 offset:4096
	ds_read_b128 v[190:193], v9 offset:5120
	ds_read_b128 v[194:197], v9 offset:6144
	ds_read_b128 v[198:201], v9 offset:7168
	s_add_i32 s61, s61, 0x20380
	s_mov_b32 m0, s48
	s_nop 0
	buffer_load_dwordx4 v6, s[12:15], s61 offen lds
	s_nop 0
	s_mov_b32 m0, s49
	s_nop 0
	buffer_load_dwordx4 v7, s[12:15], s61 offen lds
	s_waitcnt vmcnt(8)
	s_waitcnt lgkmcnt(0)
	s_barrier
	s_setprio 1
	s_waitcnt lgkmcnt(7)
	v_mfma_i32_16x16x64_i8 v[142:145], v[10:13], v[170:173], v[142:145]
	v_mfma_i32_16x16x64_i8 v[138:141], v[146:149], v[170:173], v[138:141]
	s_waitcnt lgkmcnt(5)
	v_mfma_i32_16x16x64_i8 v[126:129], v[10:13], v[178:181], v[126:129]
	v_mfma_i32_16x16x64_i8 v[122:125], v[146:149], v[178:181], v[122:125]
	s_waitcnt lgkmcnt(3)
	v_mfma_i32_16x16x64_i8 v[110:113], v[10:13], v[186:189], v[110:113]
	v_mfma_i32_16x16x64_i8 v[106:109], v[146:149], v[186:189], v[106:109]
	s_waitcnt lgkmcnt(1)
	v_mfma_i32_16x16x64_i8 v[94:97], v[10:13], v[194:197], v[94:97]
	v_mfma_i32_16x16x64_i8 v[90:93], v[146:149], v[194:197], v[90:93]
	v_mfma_i32_16x16x64_i8 v[142:145], v[14:17], v[174:177], v[142:145]
	v_mfma_i32_16x16x64_i8 v[138:141], v[150:153], v[174:177], v[138:141]
	v_mfma_i32_16x16x64_i8 v[126:129], v[14:17], v[182:185], v[126:129]
	v_mfma_i32_16x16x64_i8 v[122:125], v[150:153], v[182:185], v[122:125]
	v_mfma_i32_16x16x64_i8 v[110:113], v[14:17], v[190:193], v[110:113]
	v_mfma_i32_16x16x64_i8 v[106:109], v[150:153], v[190:193], v[106:109]
	s_waitcnt lgkmcnt(0)
	v_mfma_i32_16x16x64_i8 v[94:97], v[14:17], v[198:201], v[94:97]
	v_mfma_i32_16x16x64_i8 v[90:93], v[150:153], v[198:201], v[90:93]
	s_setprio 0
	s_setprio 1
	v_mfma_i32_16x16x64_i8 v[134:137], v[154:157], v[170:173], v[134:137]
	v_mfma_i32_16x16x64_i8 v[130:133], v[162:165], v[170:173], v[130:133]
	v_mfma_i32_16x16x64_i8 v[118:121], v[154:157], v[178:181], v[118:121]
	v_mfma_i32_16x16x64_i8 v[114:117], v[162:165], v[178:181], v[114:117]
	v_mfma_i32_16x16x64_i8 v[102:105], v[154:157], v[186:189], v[102:105]
	v_mfma_i32_16x16x64_i8 v[98:101], v[162:165], v[186:189], v[98:101]
	v_mfma_i32_16x16x64_i8 v[86:89], v[154:157], v[194:197], v[86:89]
	v_mfma_i32_16x16x64_i8 v[82:85], v[162:165], v[194:197], v[82:85]
	v_mfma_i32_16x16x64_i8 v[134:137], v[158:161], v[174:177], v[134:137]
	v_mfma_i32_16x16x64_i8 v[130:133], v[166:169], v[174:177], v[130:133]
	v_mfma_i32_16x16x64_i8 v[118:121], v[158:161], v[182:185], v[118:121]
	v_mfma_i32_16x16x64_i8 v[114:117], v[166:169], v[182:185], v[114:117]
	v_mfma_i32_16x16x64_i8 v[102:105], v[158:161], v[190:193], v[102:105]
	v_mfma_i32_16x16x64_i8 v[98:101], v[166:169], v[190:193], v[98:101]
	v_mfma_i32_16x16x64_i8 v[86:89], v[158:161], v[198:201], v[86:89]
	v_mfma_i32_16x16x64_i8 v[82:85], v[166:169], v[198:201], v[82:85]
	s_setprio 0
	s_barrier
	ds_read_b128 v[170:173], v9 offset:16384
	ds_read_b128 v[174:177], v9 offset:17408
	s_mov_b32 m0, s29
	s_nop 0
	buffer_load_dwordx4 v6, s[8:11], s60 offen lds
	ds_read_b128 v[178:181], v9 offset:18432
	ds_read_b128 v[182:185], v9 offset:19456
	s_add_i32 s61, s60, 0x20000
	s_mov_b32 m0, s34
	s_nop 0
	buffer_load_dwordx4 v7, s[8:11], s60 offen lds
	ds_read_b128 v[186:189], v9 offset:20480
	ds_read_b128 v[190:193], v9 offset:21504
	s_nop 0
	s_mov_b32 m0, s35
	s_nop 0
	buffer_load_dwordx4 v6, s[8:11], s61 offen lds
	ds_read_b128 v[194:197], v9 offset:22528
	ds_read_b128 v[198:201], v9 offset:23552
	s_nop 0
	s_mov_b32 m0, s36
	s_nop 0
	buffer_load_dwordx4 v7, s[8:11], s61 offen lds
	s_nop 0
	s_mov_b32 m0, s28
	s_nop 0
	buffer_load_dwordx4 v6, s[12:15], s62 offen lds
	s_nop 0
	s_mov_b32 m0, s38
	s_nop 0
	buffer_load_dwordx4 v7, s[12:15], s62 offen lds
	s_waitcnt vmcnt(8)
	s_waitcnt lgkmcnt(0)
	s_barrier
	s_setprio 1
	s_waitcnt lgkmcnt(7)
	v_mfma_i32_16x16x64_i8 v[78:81], v[10:13], v[170:173], v[78:81]
	v_mfma_i32_16x16x64_i8 v[74:77], v[146:149], v[170:173], v[74:77]
	s_waitcnt lgkmcnt(5)
	v_mfma_i32_16x16x64_i8 v[62:65], v[10:13], v[178:181], v[62:65]
	v_mfma_i32_16x16x64_i8 v[58:61], v[146:149], v[178:181], v[58:61]
	s_waitcnt lgkmcnt(3)
	v_mfma_i32_16x16x64_i8 v[46:49], v[10:13], v[186:189], v[46:49]
	v_mfma_i32_16x16x64_i8 v[42:45], v[146:149], v[186:189], v[42:45]
	s_waitcnt lgkmcnt(1)
	v_mfma_i32_16x16x64_i8 v[10:13], v[10:13], v[194:197], v[30:33]
	v_mfma_i32_16x16x64_i8 v[78:81], v[14:17], v[174:177], v[78:81]
	v_mfma_i32_16x16x64_i8 v[74:77], v[150:153], v[174:177], v[74:77]
	v_mfma_i32_16x16x64_i8 v[62:65], v[14:17], v[182:185], v[62:65]
	v_mfma_i32_16x16x64_i8 v[58:61], v[150:153], v[182:185], v[58:61]
	v_mfma_i32_16x16x64_i8 v[46:49], v[14:17], v[190:193], v[46:49]
	v_mfma_i32_16x16x64_i8 v[42:45], v[150:153], v[190:193], v[42:45]
	s_waitcnt lgkmcnt(0)
	v_mfma_i32_16x16x64_i8 v[10:13], v[14:17], v[198:201], v[10:13]
	v_mfma_i32_16x16x64_i8 v[14:17], v[146:149], v[194:197], v[26:29]
	v_mfma_i32_16x16x64_i8 v[14:17], v[150:153], v[198:201], v[14:17]
	s_setprio 0
	s_setprio 1
	v_mfma_i32_16x16x64_i8 v[26:29], v[154:157], v[170:173], v[70:73]
	v_mfma_i32_16x16x64_i8 v[70:73], v[158:161], v[174:177], v[26:29]
	v_mfma_i32_16x16x64_i8 v[26:29], v[162:165], v[170:173], v[66:69]
	v_mfma_i32_16x16x64_i8 v[66:69], v[166:169], v[174:177], v[26:29]
	v_mfma_i32_16x16x64_i8 v[26:29], v[154:157], v[178:181], v[54:57]
	v_mfma_i32_16x16x64_i8 v[54:57], v[158:161], v[182:185], v[26:29]
	v_mfma_i32_16x16x64_i8 v[26:29], v[162:165], v[178:181], v[50:53]
	v_mfma_i32_16x16x64_i8 v[50:53], v[166:169], v[182:185], v[26:29]
	v_mfma_i32_16x16x64_i8 v[26:29], v[154:157], v[186:189], v[38:41]
	v_mfma_i32_16x16x64_i8 v[38:41], v[158:161], v[190:193], v[26:29]
	v_mfma_i32_16x16x64_i8 v[26:29], v[162:165], v[186:189], v[34:37]
	v_mfma_i32_16x16x64_i8 v[22:25], v[154:157], v[194:197], v[22:25]
	v_mfma_i32_16x16x64_i8 v[18:21], v[162:165], v[194:197], v[18:21]
	v_mfma_i32_16x16x64_i8 v[34:37], v[166:169], v[190:193], v[26:29]
	v_mfma_i32_16x16x64_i8 v[22:25], v[158:161], v[198:201], v[22:25]
	v_mfma_i32_16x16x64_i8 v[18:21], v[166:169], v[198:201], v[18:21]
	s_setprio 0
	s_barrier
	v_add_u32_e32 v150, 0x18000, v8
	v_add_u32_e32 v166, 0x1c000, v8
	ds_read_b128 v[26:29], v150
	ds_read_b128 v[30:33], v150 offset:1024
	ds_read_b128 v[146:149], v150 offset:2048
	ds_read_b128 v[150:153], v150 offset:3072
	ds_read_b128 v[154:157], v166
	ds_read_b128 v[158:161], v166 offset:1024
	ds_read_b128 v[162:165], v166 offset:2048
	ds_read_b128 v[166:169], v166 offset:3072
	ds_read_b128 v[170:173], v9 offset:32768
	ds_read_b128 v[174:177], v9 offset:33792
	ds_read_b128 v[178:181], v9 offset:34816
	ds_read_b128 v[182:185], v9 offset:35840
	ds_read_b128 v[186:189], v9 offset:36864
	ds_read_b128 v[190:193], v9 offset:37888
	ds_read_b128 v[194:197], v9 offset:38912
	ds_read_b128 v[198:201], v9 offset:39936
	s_add_i32 s61, s62, 0x20000
	s_mov_b32 m0, s40
	s_nop 0
	buffer_load_dwordx4 v6, s[12:15], s61 offen lds
	s_nop 0
	s_mov_b32 m0, s41
	s_nop 0
	buffer_load_dwordx4 v7, s[12:15], s61 offen lds
	s_waitcnt vmcnt(8)
	s_waitcnt lgkmcnt(0)
	s_barrier
	s_setprio 1
	s_waitcnt lgkmcnt(7)
	v_mfma_i32_16x16x64_i8 v[142:145], v[26:29], v[170:173], v[142:145]
	v_mfma_i32_16x16x64_i8 v[138:141], v[146:149], v[170:173], v[138:141]
	s_waitcnt lgkmcnt(5)
	v_mfma_i32_16x16x64_i8 v[126:129], v[26:29], v[178:181], v[126:129]
	v_mfma_i32_16x16x64_i8 v[122:125], v[146:149], v[178:181], v[122:125]
	s_waitcnt lgkmcnt(3)
	v_mfma_i32_16x16x64_i8 v[110:113], v[26:29], v[186:189], v[110:113]
	v_mfma_i32_16x16x64_i8 v[106:109], v[146:149], v[186:189], v[106:109]
	s_waitcnt lgkmcnt(1)
	v_mfma_i32_16x16x64_i8 v[94:97], v[26:29], v[194:197], v[94:97]
	v_mfma_i32_16x16x64_i8 v[90:93], v[146:149], v[194:197], v[90:93]
	v_mfma_i32_16x16x64_i8 v[142:145], v[30:33], v[174:177], v[142:145]
	v_mfma_i32_16x16x64_i8 v[138:141], v[150:153], v[174:177], v[138:141]
	v_mfma_i32_16x16x64_i8 v[126:129], v[30:33], v[182:185], v[126:129]
	v_mfma_i32_16x16x64_i8 v[122:125], v[150:153], v[182:185], v[122:125]
	v_mfma_i32_16x16x64_i8 v[110:113], v[30:33], v[190:193], v[110:113]
	v_mfma_i32_16x16x64_i8 v[106:109], v[150:153], v[190:193], v[106:109]
	s_waitcnt lgkmcnt(0)
	v_mfma_i32_16x16x64_i8 v[94:97], v[30:33], v[198:201], v[94:97]
	v_mfma_i32_16x16x64_i8 v[90:93], v[150:153], v[198:201], v[90:93]
	s_setprio 0
	s_setprio 1
	v_mfma_i32_16x16x64_i8 v[134:137], v[154:157], v[170:173], v[134:137]
	v_mfma_i32_16x16x64_i8 v[130:133], v[162:165], v[170:173], v[130:133]
	v_mfma_i32_16x16x64_i8 v[118:121], v[154:157], v[178:181], v[118:121]
	v_mfma_i32_16x16x64_i8 v[114:117], v[162:165], v[178:181], v[114:117]
	v_mfma_i32_16x16x64_i8 v[102:105], v[154:157], v[186:189], v[102:105]
	v_mfma_i32_16x16x64_i8 v[98:101], v[162:165], v[186:189], v[98:101]
	v_mfma_i32_16x16x64_i8 v[86:89], v[154:157], v[194:197], v[86:89]
	v_mfma_i32_16x16x64_i8 v[82:85], v[162:165], v[194:197], v[82:85]
	v_mfma_i32_16x16x64_i8 v[134:137], v[158:161], v[174:177], v[134:137]
	v_mfma_i32_16x16x64_i8 v[130:133], v[166:169], v[174:177], v[130:133]
	v_mfma_i32_16x16x64_i8 v[118:121], v[158:161], v[182:185], v[118:121]
	v_mfma_i32_16x16x64_i8 v[114:117], v[166:169], v[182:185], v[114:117]
	v_mfma_i32_16x16x64_i8 v[102:105], v[158:161], v[190:193], v[102:105]
	v_mfma_i32_16x16x64_i8 v[98:101], v[166:169], v[190:193], v[98:101]
	v_mfma_i32_16x16x64_i8 v[86:89], v[158:161], v[198:201], v[86:89]
	v_mfma_i32_16x16x64_i8 v[82:85], v[166:169], v[198:201], v[82:85]
	s_setprio 0
	s_barrier
	ds_read_b128 v[170:173], v9 offset:49152
	ds_read_b128 v[174:177], v9 offset:50176
	s_or_b32 s61, s60, 0x80
	s_mov_b32 m0, s42
	s_nop 0
	buffer_load_dwordx4 v6, s[8:11], s61 offen lds
	ds_read_b128 v[178:181], v9 offset:51200
	ds_read_b128 v[182:185], v9 offset:52224
	s_add_i32 s60, s60, 0x20080
	s_mov_b32 m0, s43
	s_nop 0
	buffer_load_dwordx4 v7, s[8:11], s61 offen lds
	ds_read_b128 v[186:189], v9 offset:53248
	ds_read_b128 v[190:193], v9 offset:54272
	s_nop 0
	s_mov_b32 m0, s46
	s_nop 0
	buffer_load_dwordx4 v6, s[8:11], s60 offen lds
	ds_read_b128 v[194:197], v9 offset:55296
	ds_read_b128 v[198:201], v9 offset:56320
	s_nop 0
	s_mov_b32 m0, s47
	s_nop 0
	buffer_load_dwordx4 v7, s[8:11], s60 offen lds
	s_nop 0
	s_mov_b32 m0, s44
	s_nop 0
	buffer_load_dwordx4 v6, s[12:15], s59 offen lds
	s_nop 0
	s_mov_b32 m0, s45
	s_nop 0
	buffer_load_dwordx4 v7, s[12:15], s59 offen lds
	s_waitcnt vmcnt(8)
	s_waitcnt lgkmcnt(0)
	s_barrier
	s_setprio 1
	s_waitcnt lgkmcnt(7)
	v_mfma_i32_16x16x64_i8 v[78:81], v[26:29], v[170:173], v[78:81]
	s_waitcnt lgkmcnt(5)
	v_mfma_i32_16x16x64_i8 v[62:65], v[26:29], v[178:181], v[62:65]
	s_waitcnt lgkmcnt(3)
	v_mfma_i32_16x16x64_i8 v[46:49], v[26:29], v[186:189], v[46:49]
	s_waitcnt lgkmcnt(1)
	v_mfma_i32_16x16x64_i8 v[10:13], v[26:29], v[194:197], v[10:13]
	v_mfma_i32_16x16x64_i8 v[78:81], v[30:33], v[174:177], v[78:81]
	v_mfma_i32_16x16x64_i8 v[74:77], v[146:149], v[170:173], v[74:77]
	v_mfma_i32_16x16x64_i8 v[62:65], v[30:33], v[182:185], v[62:65]
	v_mfma_i32_16x16x64_i8 v[58:61], v[146:149], v[178:181], v[58:61]
	v_mfma_i32_16x16x64_i8 v[46:49], v[30:33], v[190:193], v[46:49]
	v_mfma_i32_16x16x64_i8 v[42:45], v[146:149], v[186:189], v[42:45]
	s_waitcnt lgkmcnt(0)
	v_mfma_i32_16x16x64_i8 v[30:33], v[30:33], v[198:201], v[10:13]
	v_mfma_i32_16x16x64_i8 v[10:13], v[146:149], v[194:197], v[14:17]
	v_mfma_i32_16x16x64_i8 v[74:77], v[150:153], v[174:177], v[74:77]
	v_mfma_i32_16x16x64_i8 v[58:61], v[150:153], v[182:185], v[58:61]
	v_mfma_i32_16x16x64_i8 v[42:45], v[150:153], v[190:193], v[42:45]
	v_mfma_i32_16x16x64_i8 v[26:29], v[150:153], v[198:201], v[10:13]
	s_setprio 0
	s_setprio 1
	v_mfma_i32_16x16x64_i8 v[10:13], v[154:157], v[170:173], v[70:73]
	v_mfma_i32_16x16x64_i8 v[70:73], v[158:161], v[174:177], v[10:13]
	v_mfma_i32_16x16x64_i8 v[10:13], v[162:165], v[170:173], v[66:69]
	v_mfma_i32_16x16x64_i8 v[66:69], v[166:169], v[174:177], v[10:13]
	v_mfma_i32_16x16x64_i8 v[10:13], v[154:157], v[178:181], v[54:57]
	v_mfma_i32_16x16x64_i8 v[54:57], v[158:161], v[182:185], v[10:13]
	v_mfma_i32_16x16x64_i8 v[10:13], v[162:165], v[178:181], v[50:53]
	v_mfma_i32_16x16x64_i8 v[50:53], v[166:169], v[182:185], v[10:13]
	v_mfma_i32_16x16x64_i8 v[10:13], v[154:157], v[186:189], v[38:41]
	v_mfma_i32_16x16x64_i8 v[38:41], v[158:161], v[190:193], v[10:13]
	v_mfma_i32_16x16x64_i8 v[10:13], v[162:165], v[186:189], v[34:37]
	v_mfma_i32_16x16x64_i8 v[34:37], v[166:169], v[190:193], v[10:13]
	v_mfma_i32_16x16x64_i8 v[10:13], v[154:157], v[194:197], v[22:25]
	v_mfma_i32_16x16x64_i8 v[22:25], v[158:161], v[198:201], v[10:13]
	v_mfma_i32_16x16x64_i8 v[10:13], v[162:165], v[194:197], v[18:21]
	v_mfma_i32_16x16x64_i8 v[18:21], v[166:169], v[198:201], v[10:13]
	s_setprio 0
	s_barrier
	s_add_i32 s55, s55, 2
	s_addk_i32 s58, 0x100
	s_cmp_lt_u32 s55, 6
	s_cbranch_scc1 .LBB0_943
	s_andn2_b64 vcc, exec, s[6:7]
	s_cbranch_vccz .LBB0_935
	v_cvt_f32_i32_e32 v142, v142
	v_cvt_f32_i32_e32 v143, v143
	v_cvt_f32_i32_e32 v144, v144
	v_cvt_f32_i32_e32 v145, v145
	v_cvt_f32_i32_e32 v138, v138
	v_cvt_f32_i32_e32 v139, v139
	v_cvt_f32_i32_e32 v140, v140
	v_cvt_f32_i32_e32 v141, v141
	v_cvt_f32_i32_e32 v126, v126
	v_cvt_f32_i32_e32 v127, v127
	v_cvt_f32_i32_e32 v128, v128
	v_cvt_f32_i32_e32 v129, v129
	v_cvt_f32_i32_e32 v122, v122
	v_cvt_f32_i32_e32 v123, v123
	v_cvt_f32_i32_e32 v124, v124
	v_cvt_f32_i32_e32 v125, v125
	v_cvt_f32_i32_e32 v110, v110
	v_cvt_f32_i32_e32 v111, v111
	v_cvt_f32_i32_e32 v112, v112
	v_cvt_f32_i32_e32 v113, v113
	v_cvt_f32_i32_e32 v106, v106
	v_cvt_f32_i32_e32 v107, v107
	v_cvt_f32_i32_e32 v108, v108
	v_cvt_f32_i32_e32 v109, v109
	v_cvt_f32_i32_e32 v94, v94
	v_cvt_f32_i32_e32 v95, v95
	v_cvt_f32_i32_e32 v96, v96
	v_cvt_f32_i32_e32 v97, v97
	v_cvt_f32_i32_e32 v90, v90
	v_cvt_f32_i32_e32 v91, v91
	v_cvt_f32_i32_e32 v92, v92
	v_cvt_f32_i32_e32 v93, v93
	v_cvt_f32_i32_e32 v134, v134
	v_cvt_f32_i32_e32 v135, v135
	v_cvt_f32_i32_e32 v136, v136
	v_cvt_f32_i32_e32 v137, v137
	v_cvt_f32_i32_e32 v130, v130
	v_cvt_f32_i32_e32 v131, v131
	v_cvt_f32_i32_e32 v132, v132
	v_cvt_f32_i32_e32 v133, v133
	v_cvt_f32_i32_e32 v118, v118
	v_cvt_f32_i32_e32 v119, v119
	v_cvt_f32_i32_e32 v120, v120
	v_cvt_f32_i32_e32 v121, v121
	v_cvt_f32_i32_e32 v114, v114
	v_cvt_f32_i32_e32 v115, v115
	v_cvt_f32_i32_e32 v116, v116
	v_cvt_f32_i32_e32 v117, v117
	v_cvt_f32_i32_e32 v102, v102
	v_cvt_f32_i32_e32 v103, v103
	v_cvt_f32_i32_e32 v104, v104
	v_cvt_f32_i32_e32 v105, v105
	v_cvt_f32_i32_e32 v98, v98
	v_cvt_f32_i32_e32 v99, v99
	v_cvt_f32_i32_e32 v100, v100
	v_cvt_f32_i32_e32 v101, v101
	v_cvt_f32_i32_e32 v86, v86
	v_cvt_f32_i32_e32 v87, v87
	v_cvt_f32_i32_e32 v88, v88
	v_cvt_f32_i32_e32 v89, v89
	v_cvt_f32_i32_e32 v82, v82
	v_cvt_f32_i32_e32 v83, v83
	v_cvt_f32_i32_e32 v84, v84
	v_cvt_f32_i32_e32 v85, v85
	v_cvt_f32_i32_e32 v78, v78
	v_cvt_f32_i32_e32 v79, v79
	v_cvt_f32_i32_e32 v80, v80
	v_cvt_f32_i32_e32 v81, v81
	v_cvt_f32_i32_e32 v74, v74
	v_cvt_f32_i32_e32 v75, v75
	v_cvt_f32_i32_e32 v76, v76
	v_cvt_f32_i32_e32 v77, v77
	v_cvt_f32_i32_e32 v62, v62
	v_cvt_f32_i32_e32 v63, v63
	v_cvt_f32_i32_e32 v64, v64
	v_cvt_f32_i32_e32 v65, v65
	v_cvt_f32_i32_e32 v58, v58
	v_cvt_f32_i32_e32 v59, v59
	v_cvt_f32_i32_e32 v60, v60
	v_cvt_f32_i32_e32 v61, v61
	v_cvt_f32_i32_e32 v46, v46
	v_cvt_f32_i32_e32 v47, v47
	v_cvt_f32_i32_e32 v48, v48
	v_cvt_f32_i32_e32 v49, v49
	v_cvt_f32_i32_e32 v42, v42
	v_cvt_f32_i32_e32 v43, v43
	v_cvt_f32_i32_e32 v44, v44
	v_cvt_f32_i32_e32 v45, v45
	v_cvt_f32_i32_e32 v30, v30
	v_cvt_f32_i32_e32 v31, v31
	v_cvt_f32_i32_e32 v32, v32
	v_cvt_f32_i32_e32 v33, v33
	v_cvt_f32_i32_e32 v26, v26
	v_cvt_f32_i32_e32 v27, v27
	v_cvt_f32_i32_e32 v28, v28
	v_cvt_f32_i32_e32 v29, v29
	v_cvt_f32_i32_e32 v70, v70
	v_cvt_f32_i32_e32 v71, v71
	v_cvt_f32_i32_e32 v72, v72
	v_cvt_f32_i32_e32 v73, v73
	v_cvt_f32_i32_e32 v66, v66
	v_cvt_f32_i32_e32 v67, v67
	v_cvt_f32_i32_e32 v68, v68
	v_cvt_f32_i32_e32 v69, v69
	v_cvt_f32_i32_e32 v54, v54
	v_cvt_f32_i32_e32 v55, v55
	v_cvt_f32_i32_e32 v56, v56
	v_cvt_f32_i32_e32 v57, v57
	v_cvt_f32_i32_e32 v50, v50
	v_cvt_f32_i32_e32 v51, v51
	v_cvt_f32_i32_e32 v52, v52
	v_cvt_f32_i32_e32 v53, v53
	v_cvt_f32_i32_e32 v38, v38
	v_cvt_f32_i32_e32 v39, v39
	v_cvt_f32_i32_e32 v40, v40
	v_cvt_f32_i32_e32 v41, v41
	v_cvt_f32_i32_e32 v34, v34
	v_cvt_f32_i32_e32 v35, v35
	v_cvt_f32_i32_e32 v36, v36
	v_cvt_f32_i32_e32 v37, v37
	v_cvt_f32_i32_e32 v22, v22
	v_cvt_f32_i32_e32 v23, v23
	v_cvt_f32_i32_e32 v24, v24
	v_cvt_f32_i32_e32 v25, v25
	v_cvt_f32_i32_e32 v18, v18
	v_cvt_f32_i32_e32 v19, v19
	v_cvt_f32_i32_e32 v20, v20
	v_cvt_f32_i32_e32 v21, v21
	s_andn2_b64 vcc, exec, s[4:5]
	s_cbranch_vccnz .LBB0_936

.LBB0_1072:
	ds_read_b128 v[136:139], v152
	ds_read_b128 v[140:143], v152 offset:1024
	ds_read_b128 v[158:161], v152 offset:2048
	ds_read_b128 v[162:165], v152 offset:3072
	ds_read_b128 v[166:169], v153
	ds_read_b128 v[170:173], v153 offset:1024
	ds_read_b128 v[174:177], v153 offset:2048
	ds_read_b128 v[178:181], v153 offset:3072
	s_add_i32 s60, s55, 0xfffe0080
	s_cmp_eq_u32 s59, 4
	s_cselect_b32 s62, s1, s60
	s_cselect_b32 s61, s54, s58
	s_or_b32 s60, s62, 0x80
	ds_read_b128 v[182:185], v154
	ds_read_b128 v[186:189], v154 offset:1024
	ds_read_b128 v[190:193], v154 offset:2048
	ds_read_b128 v[194:197], v154 offset:3072
	ds_read_b128 v[198:201], v154 offset:4096
	ds_read_b128 v[202:205], v154 offset:5120
	ds_read_b128 v[206:209], v154 offset:6144
	ds_read_b128 v[210:213], v154 offset:7168
	s_mov_b32 m0, s42
	s_nop 0
	buffer_load_dwordx4 v146, s[12:15], s55 offen lds
	s_nop 0
	s_mov_b32 m0, s43
	s_nop 0
	buffer_load_dwordx4 v147, s[12:15], s55 offen lds
	s_waitcnt vmcnt(8)
	s_waitcnt lgkmcnt(0)
	s_barrier
	s_setprio 1
	s_waitcnt lgkmcnt(0)
	v_mfma_i32_16x16x64_i8 v[126:129], v[136:139], v[182:185], v[126:129]
	v_mfma_i32_16x16x64_i8 v[122:125], v[158:161], v[182:185], v[122:125]
	v_mfma_i32_16x16x64_i8 v[118:121], v[136:139], v[190:193], v[118:121]
	v_mfma_i32_16x16x64_i8 v[114:117], v[158:161], v[190:193], v[114:117]
	v_mfma_i32_16x16x64_i8 v[110:113], v[136:139], v[198:201], v[110:113]
	v_mfma_i32_16x16x64_i8 v[106:109], v[158:161], v[198:201], v[106:109]
	v_mfma_i32_16x16x64_i8 v[102:105], v[136:139], v[206:209], v[102:105]
	v_mfma_i32_16x16x64_i8 v[98:101], v[158:161], v[206:209], v[98:101]
	v_mfma_i32_16x16x64_i8 v[126:129], v[140:143], v[186:189], v[126:129]
	v_mfma_i32_16x16x64_i8 v[122:125], v[162:165], v[186:189], v[122:125]
	v_mfma_i32_16x16x64_i8 v[118:121], v[140:143], v[194:197], v[118:121]
	v_mfma_i32_16x16x64_i8 v[114:117], v[162:165], v[194:197], v[114:117]
	v_mfma_i32_16x16x64_i8 v[110:113], v[140:143], v[202:205], v[110:113]
	v_mfma_i32_16x16x64_i8 v[106:109], v[162:165], v[202:205], v[106:109]
	v_mfma_i32_16x16x64_i8 v[102:105], v[140:143], v[210:213], v[102:105]
	v_mfma_i32_16x16x64_i8 v[98:101], v[162:165], v[210:213], v[98:101]
	s_setprio 0
	s_setprio 1
	v_mfma_i32_16x16x64_i8 v[94:97], v[166:169], v[182:185], v[94:97]
	v_mfma_i32_16x16x64_i8 v[90:93], v[174:177], v[182:185], v[90:93]
	v_mfma_i32_16x16x64_i8 v[86:89], v[166:169], v[190:193], v[86:89]
	v_mfma_i32_16x16x64_i8 v[82:85], v[174:177], v[190:193], v[82:85]
	v_mfma_i32_16x16x64_i8 v[78:81], v[166:169], v[198:201], v[78:81]
	v_mfma_i32_16x16x64_i8 v[74:77], v[174:177], v[198:201], v[74:77]
	v_mfma_i32_16x16x64_i8 v[70:73], v[166:169], v[206:209], v[70:73]
	v_mfma_i32_16x16x64_i8 v[66:69], v[174:177], v[206:209], v[66:69]
	v_mfma_i32_16x16x64_i8 v[94:97], v[170:173], v[186:189], v[94:97]
	v_mfma_i32_16x16x64_i8 v[90:93], v[178:181], v[186:189], v[90:93]
	v_mfma_i32_16x16x64_i8 v[86:89], v[170:173], v[194:197], v[86:89]
	v_mfma_i32_16x16x64_i8 v[82:85], v[178:181], v[194:197], v[82:85]
	v_mfma_i32_16x16x64_i8 v[78:81], v[170:173], v[202:205], v[78:81]
	v_mfma_i32_16x16x64_i8 v[74:77], v[178:181], v[202:205], v[74:77]
	v_mfma_i32_16x16x64_i8 v[70:73], v[170:173], v[210:213], v[70:73]
	v_mfma_i32_16x16x64_i8 v[66:69], v[178:181], v[210:213], v[66:69]
	s_setprio 0
	s_barrier
	ds_read_b128 v[182:185], v154 offset:16384
	ds_read_b128 v[186:189], v154 offset:17408
	s_mov_b32 m0, s27
	s_nop 0
	buffer_load_dwordx4 v144, s[8:11], s61 offen lds
	ds_read_b128 v[190:193], v154 offset:18432
	ds_read_b128 v[194:197], v154 offset:19456
	s_add_i32 s63, s61, 0x20000
	s_mov_b32 m0, s28
	s_nop 0
	buffer_load_dwordx4 v145, s[8:11], s61 offen lds
	ds_read_b128 v[198:201], v154 offset:20480
	ds_read_b128 v[202:205], v154 offset:21504
	s_nop 0
	s_mov_b32 m0, s29
	s_nop 0
	buffer_load_dwordx4 v144, s[8:11], s63 offen lds
	ds_read_b128 v[206:209], v154 offset:22528
	ds_read_b128 v[210:213], v154 offset:23552
	s_nop 0
	s_mov_b32 m0, s30
	s_nop 0
	buffer_load_dwordx4 v145, s[8:11], s63 offen lds
	s_nop 0
	s_mov_b32 m0, s26
	s_nop 0
	buffer_load_dwordx4 v146, s[12:15], s62 offen lds
	s_nop 0
	s_mov_b32 m0, s2
	s_nop 0
	buffer_load_dwordx4 v147, s[12:15], s62 offen lds
	s_waitcnt vmcnt(8)
	s_waitcnt lgkmcnt(0)
	s_barrier
	s_setprio 1
	s_waitcnt lgkmcnt(0)
	v_mfma_i32_16x16x64_i8 v[62:65], v[136:139], v[182:185], v[62:65]
	v_mfma_i32_16x16x64_i8 v[58:61], v[158:161], v[182:185], v[58:61]
	v_mfma_i32_16x16x64_i8 v[54:57], v[136:139], v[190:193], v[54:57]
	v_mfma_i32_16x16x64_i8 v[50:53], v[158:161], v[190:193], v[50:53]
	v_mfma_i32_16x16x64_i8 v[46:49], v[136:139], v[198:201], v[46:49]
	v_mfma_i32_16x16x64_i8 v[42:45], v[158:161], v[198:201], v[42:45]
	v_mfma_i32_16x16x64_i8 v[38:41], v[136:139], v[206:209], v[38:41]
	v_mfma_i32_16x16x64_i8 v[34:37], v[158:161], v[206:209], v[34:37]
	v_mfma_i32_16x16x64_i8 v[62:65], v[140:143], v[186:189], v[62:65]
	v_mfma_i32_16x16x64_i8 v[58:61], v[162:165], v[186:189], v[58:61]
	v_mfma_i32_16x16x64_i8 v[54:57], v[140:143], v[194:197], v[54:57]
	v_mfma_i32_16x16x64_i8 v[50:53], v[162:165], v[194:197], v[50:53]
	v_mfma_i32_16x16x64_i8 v[46:49], v[140:143], v[202:205], v[46:49]
	v_mfma_i32_16x16x64_i8 v[42:45], v[162:165], v[202:205], v[42:45]
	v_mfma_i32_16x16x64_i8 v[38:41], v[140:143], v[210:213], v[38:41]
	v_mfma_i32_16x16x64_i8 v[34:37], v[162:165], v[210:213], v[34:37]
	s_setprio 0
	s_setprio 1
	v_mfma_i32_16x16x64_i8 v[30:33], v[166:169], v[182:185], v[30:33]
	v_mfma_i32_16x16x64_i8 v[26:29], v[174:177], v[182:185], v[26:29]
	v_mfma_i32_16x16x64_i8 v[22:25], v[166:169], v[190:193], v[22:25]
	v_mfma_i32_16x16x64_i8 v[18:21], v[174:177], v[190:193], v[18:21]
	v_mfma_i32_16x16x64_i8 v[14:17], v[166:169], v[198:201], v[14:17]
	v_mfma_i32_16x16x64_i8 v[10:13], v[174:177], v[198:201], v[10:13]
	v_mfma_i32_16x16x64_i8 v[6:9], v[166:169], v[206:209], v[6:9]
	v_mfma_i32_16x16x64_i8 v[2:5], v[174:177], v[206:209], v[2:5]
	v_mfma_i32_16x16x64_i8 v[30:33], v[170:173], v[186:189], v[30:33]
	v_mfma_i32_16x16x64_i8 v[26:29], v[178:181], v[186:189], v[26:29]
	v_mfma_i32_16x16x64_i8 v[22:25], v[170:173], v[194:197], v[22:25]
	v_mfma_i32_16x16x64_i8 v[18:21], v[178:181], v[194:197], v[18:21]
	v_mfma_i32_16x16x64_i8 v[14:17], v[170:173], v[202:205], v[14:17]
	v_mfma_i32_16x16x64_i8 v[10:13], v[178:181], v[202:205], v[10:13]
	v_mfma_i32_16x16x64_i8 v[6:9], v[170:173], v[210:213], v[6:9]
	v_mfma_i32_16x16x64_i8 v[2:5], v[178:181], v[210:213], v[2:5]
	s_setprio 0
	s_barrier
	ds_read_b128 v[136:139], v155
	ds_read_b128 v[140:143], v155 offset:1024
	ds_read_b128 v[158:161], v155 offset:2048
	ds_read_b128 v[162:165], v155 offset:3072
	ds_read_b128 v[166:169], v156
	ds_read_b128 v[170:173], v156 offset:1024
	ds_read_b128 v[174:177], v156 offset:2048
	ds_read_b128 v[178:181], v156 offset:3072
	ds_read_b128 v[182:185], v154 offset:32768
	ds_read_b128 v[186:189], v154 offset:33792
	ds_read_b128 v[190:193], v154 offset:34816
	ds_read_b128 v[194:197], v154 offset:35840
	ds_read_b128 v[198:201], v154 offset:36864
	ds_read_b128 v[202:205], v154 offset:37888
	ds_read_b128 v[206:209], v154 offset:38912
	ds_read_b128 v[210:213], v154 offset:39936
	s_add_i32 s62, s62, 0x20000
	s_mov_b32 m0, s3
	s_nop 0
	buffer_load_dwordx4 v146, s[12:15], s62 offen lds
	s_nop 0
	s_mov_b32 m0, s31
	s_nop 0
	buffer_load_dwordx4 v147, s[12:15], s62 offen lds
	s_waitcnt vmcnt(8)
	s_waitcnt lgkmcnt(0)
	s_barrier
	s_setprio 1
	s_waitcnt lgkmcnt(0)
	v_mfma_i32_16x16x64_i8 v[126:129], v[136:139], v[182:185], v[126:129]
	v_mfma_i32_16x16x64_i8 v[122:125], v[158:161], v[182:185], v[122:125]
	v_mfma_i32_16x16x64_i8 v[118:121], v[136:139], v[190:193], v[118:121]
	v_mfma_i32_16x16x64_i8 v[114:117], v[158:161], v[190:193], v[114:117]
	v_mfma_i32_16x16x64_i8 v[110:113], v[136:139], v[198:201], v[110:113]
	v_mfma_i32_16x16x64_i8 v[106:109], v[158:161], v[198:201], v[106:109]
	v_mfma_i32_16x16x64_i8 v[102:105], v[136:139], v[206:209], v[102:105]
	v_mfma_i32_16x16x64_i8 v[98:101], v[158:161], v[206:209], v[98:101]
	v_mfma_i32_16x16x64_i8 v[126:129], v[140:143], v[186:189], v[126:129]
	v_mfma_i32_16x16x64_i8 v[122:125], v[162:165], v[186:189], v[122:125]
	v_mfma_i32_16x16x64_i8 v[118:121], v[140:143], v[194:197], v[118:121]
	v_mfma_i32_16x16x64_i8 v[114:117], v[162:165], v[194:197], v[114:117]
	v_mfma_i32_16x16x64_i8 v[110:113], v[140:143], v[202:205], v[110:113]
	v_mfma_i32_16x16x64_i8 v[106:109], v[162:165], v[202:205], v[106:109]
	v_mfma_i32_16x16x64_i8 v[102:105], v[140:143], v[210:213], v[102:105]
	v_mfma_i32_16x16x64_i8 v[98:101], v[162:165], v[210:213], v[98:101]
	s_setprio 0
	s_setprio 1
	v_mfma_i32_16x16x64_i8 v[94:97], v[166:169], v[182:185], v[94:97]
	v_mfma_i32_16x16x64_i8 v[90:93], v[174:177], v[182:185], v[90:93]
	v_mfma_i32_16x16x64_i8 v[86:89], v[166:169], v[190:193], v[86:89]
	v_mfma_i32_16x16x64_i8 v[82:85], v[174:177], v[190:193], v[82:85]
	v_mfma_i32_16x16x64_i8 v[78:81], v[166:169], v[198:201], v[78:81]
	v_mfma_i32_16x16x64_i8 v[74:77], v[174:177], v[198:201], v[74:77]
	v_mfma_i32_16x16x64_i8 v[70:73], v[166:169], v[206:209], v[70:73]
	v_mfma_i32_16x16x64_i8 v[66:69], v[174:177], v[206:209], v[66:69]
	v_mfma_i32_16x16x64_i8 v[94:97], v[170:173], v[186:189], v[94:97]
	v_mfma_i32_16x16x64_i8 v[90:93], v[178:181], v[186:189], v[90:93]
	v_mfma_i32_16x16x64_i8 v[86:89], v[170:173], v[194:197], v[86:89]
	v_mfma_i32_16x16x64_i8 v[82:85], v[178:181], v[194:197], v[82:85]
	v_mfma_i32_16x16x64_i8 v[78:81], v[170:173], v[202:205], v[78:81]
	v_mfma_i32_16x16x64_i8 v[74:77], v[178:181], v[202:205], v[74:77]
	v_mfma_i32_16x16x64_i8 v[70:73], v[170:173], v[210:213], v[70:73]
	v_mfma_i32_16x16x64_i8 v[66:69], v[178:181], v[210:213], v[66:69]
	s_setprio 0
	s_barrier
	ds_read_b128 v[182:185], v154 offset:49152
	ds_read_b128 v[186:189], v154 offset:50176
	s_or_b32 s62, s61, 0x80
	s_mov_b32 m0, s35
	s_nop 0
	buffer_load_dwordx4 v144, s[8:11], s62 offen lds
	ds_read_b128 v[190:193], v154 offset:51200
	ds_read_b128 v[194:197], v154 offset:52224
	s_add_i32 s61, s61, 0x20080
	s_mov_b32 m0, s36
	s_nop 0
	buffer_load_dwordx4 v145, s[8:11], s62 offen lds
	ds_read_b128 v[198:201], v154 offset:53248
	ds_read_b128 v[202:205], v154 offset:54272
	s_nop 0
	s_mov_b32 m0, s39
	s_nop 0
	buffer_load_dwordx4 v144, s[8:11], s61 offen lds
	ds_read_b128 v[206:209], v154 offset:55296
	ds_read_b128 v[210:213], v154 offset:56320
	s_nop 0
	s_mov_b32 m0, s40
	s_nop 0
	buffer_load_dwordx4 v145, s[8:11], s61 offen lds
	s_nop 0
	s_mov_b32 m0, s37
	s_nop 0
	buffer_load_dwordx4 v146, s[12:15], s60 offen lds
	s_nop 0
	s_mov_b32 m0, s38
	s_nop 0
	buffer_load_dwordx4 v147, s[12:15], s60 offen lds
	s_waitcnt vmcnt(8)
	s_waitcnt lgkmcnt(0)
	s_barrier
	s_setprio 1
	s_waitcnt lgkmcnt(0)
	v_mfma_i32_16x16x64_i8 v[62:65], v[136:139], v[182:185], v[62:65]
	v_mfma_i32_16x16x64_i8 v[58:61], v[158:161], v[182:185], v[58:61]
	v_mfma_i32_16x16x64_i8 v[54:57], v[136:139], v[190:193], v[54:57]
	v_mfma_i32_16x16x64_i8 v[50:53], v[158:161], v[190:193], v[50:53]
	v_mfma_i32_16x16x64_i8 v[46:49], v[136:139], v[198:201], v[46:49]
	v_mfma_i32_16x16x64_i8 v[42:45], v[158:161], v[198:201], v[42:45]
	v_mfma_i32_16x16x64_i8 v[38:41], v[136:139], v[206:209], v[38:41]
	v_mfma_i32_16x16x64_i8 v[34:37], v[158:161], v[206:209], v[34:37]
	v_mfma_i32_16x16x64_i8 v[62:65], v[140:143], v[186:189], v[62:65]
	v_mfma_i32_16x16x64_i8 v[58:61], v[162:165], v[186:189], v[58:61]
	v_mfma_i32_16x16x64_i8 v[54:57], v[140:143], v[194:197], v[54:57]
	v_mfma_i32_16x16x64_i8 v[50:53], v[162:165], v[194:197], v[50:53]
	v_mfma_i32_16x16x64_i8 v[46:49], v[140:143], v[202:205], v[46:49]
	v_mfma_i32_16x16x64_i8 v[42:45], v[162:165], v[202:205], v[42:45]
	v_mfma_i32_16x16x64_i8 v[38:41], v[140:143], v[210:213], v[38:41]
	v_mfma_i32_16x16x64_i8 v[34:37], v[162:165], v[210:213], v[34:37]
	s_setprio 0
	s_setprio 1
	v_mfma_i32_16x16x64_i8 v[30:33], v[166:169], v[182:185], v[30:33]
	v_mfma_i32_16x16x64_i8 v[26:29], v[174:177], v[182:185], v[26:29]
	v_mfma_i32_16x16x64_i8 v[22:25], v[166:169], v[190:193], v[22:25]
	v_mfma_i32_16x16x64_i8 v[18:21], v[174:177], v[190:193], v[18:21]
	v_mfma_i32_16x16x64_i8 v[14:17], v[166:169], v[198:201], v[14:17]
	v_mfma_i32_16x16x64_i8 v[10:13], v[174:177], v[198:201], v[10:13]
	v_mfma_i32_16x16x64_i8 v[6:9], v[166:169], v[206:209], v[6:9]
	v_mfma_i32_16x16x64_i8 v[2:5], v[174:177], v[206:209], v[2:5]
	v_mfma_i32_16x16x64_i8 v[30:33], v[170:173], v[186:189], v[30:33]
	v_mfma_i32_16x16x64_i8 v[26:29], v[178:181], v[186:189], v[26:29]
	v_mfma_i32_16x16x64_i8 v[22:25], v[170:173], v[194:197], v[22:25]
	v_mfma_i32_16x16x64_i8 v[18:21], v[178:181], v[194:197], v[18:21]
	v_mfma_i32_16x16x64_i8 v[14:17], v[170:173], v[202:205], v[14:17]
	v_mfma_i32_16x16x64_i8 v[10:13], v[178:181], v[202:205], v[10:13]
	v_mfma_i32_16x16x64_i8 v[6:9], v[170:173], v[210:213], v[6:9]
	v_mfma_i32_16x16x64_i8 v[2:5], v[178:181], v[210:213], v[2:5]
	s_setprio 0
	s_barrier
	s_add_i32 s59, s59, 2
	s_addk_i32 s55, 0x100
	s_addk_i32 s58, 0x100
	s_cmp_gt_u32 s59, 5
	s_cbranch_scc0 .LBB0_1072
	s_and_b64 vcc, exec, s[20:21]
	s_cbranch_vccz .LBB0_1075
	s_barrier

.LBB0_1135:
	v_add_u32_e32 v150, 0x10000, v136
	v_add_u32_e32 v166, 0x14000, v136
	ds_read_b128 v[138:141], v150
	ds_read_b128 v[142:145], v150 offset:1024
	ds_read_b128 v[146:149], v150 offset:2048
	ds_read_b128 v[150:153], v150 offset:3072
	ds_read_b128 v[154:157], v166
	ds_read_b128 v[158:161], v166 offset:1024
	ds_read_b128 v[162:165], v166 offset:2048
	ds_read_b128 v[166:169], v166 offset:3072
	s_add_i32 s57, s36, s3
	s_add_i32 s56, s30, s3
	s_add_i32 s55, s57, 0x1600
	s_addk_i32 s56, 0x1600
	s_cmp_eq_u32 s3, 0
	s_cselect_b32 s58, s53, s55
	s_cselect_b32 s56, s54, s56
	s_add_i32 s55, s58, 0x80
	ds_read_b128 v[170:173], v137
	ds_read_b128 v[174:177], v137 offset:1024
	ds_read_b128 v[178:181], v137 offset:2048
	ds_read_b128 v[182:185], v137 offset:3072
	ds_read_b128 v[186:189], v137 offset:4096
	ds_read_b128 v[190:193], v137 offset:5120
	ds_read_b128 v[194:197], v137 offset:6144
	ds_read_b128 v[198:201], v137 offset:7168
	s_add_i32 s57, s57, 0xb1580
	s_mov_b32 m0, s46
	s_nop 0
	buffer_load_dwordx4 v134, s[16:19], s57 offen lds
	s_nop 0
	s_mov_b32 m0, s47
	s_nop 0
	buffer_load_dwordx4 v135, s[16:19], s57 offen lds
	s_waitcnt vmcnt(8)
	s_waitcnt lgkmcnt(0)
	s_barrier
	s_setprio 1
	s_waitcnt lgkmcnt(7)
	v_mfma_f32_16x16x32_bf16 v[126:129], v[138:141], v[170:173], v[126:129]
	v_mfma_f32_16x16x32_bf16 v[122:125], v[146:149], v[170:173], v[122:125]
	s_waitcnt lgkmcnt(5)
	v_mfma_f32_16x16x32_bf16 v[118:121], v[138:141], v[178:181], v[118:121]
	v_mfma_f32_16x16x32_bf16 v[106:109], v[146:149], v[178:181], v[106:109]
	s_waitcnt lgkmcnt(3)
	v_mfma_f32_16x16x32_bf16 v[102:105], v[138:141], v[186:189], v[102:105]
	v_mfma_f32_16x16x32_bf16 v[90:93], v[146:149], v[186:189], v[90:93]
	s_waitcnt lgkmcnt(1)
	v_mfma_f32_16x16x32_bf16 v[86:89], v[138:141], v[194:197], v[86:89]
	v_mfma_f32_16x16x32_bf16 v[74:77], v[146:149], v[194:197], v[74:77]
	v_mfma_f32_16x16x32_bf16 v[126:129], v[142:145], v[174:177], v[126:129]
	v_mfma_f32_16x16x32_bf16 v[122:125], v[150:153], v[174:177], v[122:125]
	v_mfma_f32_16x16x32_bf16 v[118:121], v[142:145], v[182:185], v[118:121]
	v_mfma_f32_16x16x32_bf16 v[106:109], v[150:153], v[182:185], v[106:109]
	v_mfma_f32_16x16x32_bf16 v[102:105], v[142:145], v[190:193], v[102:105]
	v_mfma_f32_16x16x32_bf16 v[90:93], v[150:153], v[190:193], v[90:93]
	s_waitcnt lgkmcnt(0)
	v_mfma_f32_16x16x32_bf16 v[86:89], v[142:145], v[198:201], v[86:89]
	v_mfma_f32_16x16x32_bf16 v[74:77], v[150:153], v[198:201], v[74:77]
	s_setprio 0
	s_setprio 1
	v_mfma_f32_16x16x32_bf16 v[114:117], v[154:157], v[170:173], v[114:117]
	v_mfma_f32_16x16x32_bf16 v[110:113], v[162:165], v[170:173], v[110:113]
	v_mfma_f32_16x16x32_bf16 v[98:101], v[154:157], v[178:181], v[98:101]
	v_mfma_f32_16x16x32_bf16 v[94:97], v[162:165], v[178:181], v[94:97]
	v_mfma_f32_16x16x32_bf16 v[82:85], v[154:157], v[186:189], v[82:85]
	v_mfma_f32_16x16x32_bf16 v[78:81], v[162:165], v[186:189], v[78:81]
	v_mfma_f32_16x16x32_bf16 v[70:73], v[154:157], v[194:197], v[70:73]
	v_mfma_f32_16x16x32_bf16 v[66:69], v[162:165], v[194:197], v[66:69]
	v_mfma_f32_16x16x32_bf16 v[114:117], v[158:161], v[174:177], v[114:117]
	v_mfma_f32_16x16x32_bf16 v[110:113], v[166:169], v[174:177], v[110:113]
	v_mfma_f32_16x16x32_bf16 v[98:101], v[158:161], v[182:185], v[98:101]
	v_mfma_f32_16x16x32_bf16 v[94:97], v[166:169], v[182:185], v[94:97]
	v_mfma_f32_16x16x32_bf16 v[82:85], v[158:161], v[190:193], v[82:85]
	v_mfma_f32_16x16x32_bf16 v[78:81], v[166:169], v[190:193], v[78:81]
	v_mfma_f32_16x16x32_bf16 v[70:73], v[158:161], v[198:201], v[70:73]
	v_mfma_f32_16x16x32_bf16 v[66:69], v[166:169], v[198:201], v[66:69]
	s_setprio 0
	s_barrier
	ds_read_b128 v[170:173], v137 offset:16384
	ds_read_b128 v[174:177], v137 offset:17408
	s_mov_b32 m0, s29
	s_nop 0
	buffer_load_dwordx4 v134, s[12:15], s56 offen lds
	ds_read_b128 v[178:181], v137 offset:18432
	ds_read_b128 v[182:185], v137 offset:19456
	s_add_i32 s57, s56, 0xb0000
	s_mov_b32 m0, s33
	s_nop 0
	buffer_load_dwordx4 v135, s[12:15], s56 offen lds
	ds_read_b128 v[186:189], v137 offset:20480
	ds_read_b128 v[190:193], v137 offset:21504
	s_nop 0
	s_mov_b32 m0, s34
	s_nop 0
	buffer_load_dwordx4 v134, s[12:15], s57 offen lds
	ds_read_b128 v[194:197], v137 offset:22528
	ds_read_b128 v[198:201], v137 offset:23552
	s_nop 0
	s_mov_b32 m0, s35
	s_nop 0
	buffer_load_dwordx4 v135, s[12:15], s57 offen lds
	s_nop 0
	s_mov_b32 m0, s28
	s_nop 0
	buffer_load_dwordx4 v134, s[16:19], s58 offen lds
	s_nop 0
	s_mov_b32 m0, s37
	s_nop 0
	buffer_load_dwordx4 v135, s[16:19], s58 offen lds
	s_waitcnt vmcnt(8)
	s_waitcnt lgkmcnt(0)
	s_barrier
	s_setprio 1
	s_waitcnt lgkmcnt(7)
	v_mfma_f32_16x16x32_bf16 v[62:65], v[138:141], v[170:173], v[62:65]
	v_mfma_f32_16x16x32_bf16 v[58:61], v[146:149], v[170:173], v[58:61]
	s_waitcnt lgkmcnt(5)
	v_mfma_f32_16x16x32_bf16 v[54:57], v[138:141], v[178:181], v[54:57]
	v_mfma_f32_16x16x32_bf16 v[42:45], v[146:149], v[178:181], v[42:45]
	s_waitcnt lgkmcnt(3)
	v_mfma_f32_16x16x32_bf16 v[38:41], v[138:141], v[186:189], v[38:41]
	v_mfma_f32_16x16x32_bf16 v[26:29], v[146:149], v[186:189], v[26:29]
	s_waitcnt lgkmcnt(1)
	v_mfma_f32_16x16x32_bf16 v[18:21], v[138:141], v[194:197], v[18:21]
	v_mfma_f32_16x16x32_bf16 v[10:13], v[146:149], v[194:197], v[10:13]
	v_mfma_f32_16x16x32_bf16 v[62:65], v[142:145], v[174:177], v[62:65]
	v_mfma_f32_16x16x32_bf16 v[58:61], v[150:153], v[174:177], v[58:61]
	v_mfma_f32_16x16x32_bf16 v[54:57], v[142:145], v[182:185], v[54:57]
	v_mfma_f32_16x16x32_bf16 v[42:45], v[150:153], v[182:185], v[42:45]
	v_mfma_f32_16x16x32_bf16 v[38:41], v[142:145], v[190:193], v[38:41]
	v_mfma_f32_16x16x32_bf16 v[26:29], v[150:153], v[190:193], v[26:29]
	s_waitcnt lgkmcnt(0)
	v_mfma_f32_16x16x32_bf16 v[18:21], v[142:145], v[198:201], v[18:21]
	v_mfma_f32_16x16x32_bf16 v[10:13], v[150:153], v[198:201], v[10:13]
	s_setprio 0
	s_setprio 1
	v_mfma_f32_16x16x32_bf16 v[50:53], v[154:157], v[170:173], v[50:53]
	v_mfma_f32_16x16x32_bf16 v[46:49], v[162:165], v[170:173], v[46:49]
	v_mfma_f32_16x16x32_bf16 v[34:37], v[154:157], v[178:181], v[34:37]
	v_mfma_f32_16x16x32_bf16 v[30:33], v[162:165], v[178:181], v[30:33]
	v_mfma_f32_16x16x32_bf16 v[22:25], v[154:157], v[186:189], v[22:25]
	v_mfma_f32_16x16x32_bf16 v[14:17], v[162:165], v[186:189], v[14:17]
	v_mfma_f32_16x16x32_bf16 v[6:9], v[154:157], v[194:197], v[6:9]
	v_mfma_f32_16x16x32_bf16 v[2:5], v[162:165], v[194:197], v[2:5]
	v_mfma_f32_16x16x32_bf16 v[50:53], v[158:161], v[174:177], v[50:53]
	v_mfma_f32_16x16x32_bf16 v[46:49], v[166:169], v[174:177], v[46:49]
	v_mfma_f32_16x16x32_bf16 v[34:37], v[158:161], v[182:185], v[34:37]
	v_mfma_f32_16x16x32_bf16 v[30:33], v[166:169], v[182:185], v[30:33]
	v_mfma_f32_16x16x32_bf16 v[22:25], v[158:161], v[190:193], v[22:25]
	v_mfma_f32_16x16x32_bf16 v[14:17], v[166:169], v[190:193], v[14:17]
	v_mfma_f32_16x16x32_bf16 v[6:9], v[158:161], v[198:201], v[6:9]
	v_mfma_f32_16x16x32_bf16 v[2:5], v[166:169], v[198:201], v[2:5]
	s_setprio 0
	s_barrier
	v_add_u32_e32 v150, 0x18000, v136
	v_add_u32_e32 v166, 0x1c000, v136
	ds_read_b128 v[138:141], v150
	ds_read_b128 v[142:145], v150 offset:1024
	ds_read_b128 v[146:149], v150 offset:2048
	ds_read_b128 v[150:153], v150 offset:3072
	ds_read_b128 v[154:157], v166
	ds_read_b128 v[158:161], v166 offset:1024
	ds_read_b128 v[162:165], v166 offset:2048
	ds_read_b128 v[166:169], v166 offset:3072
	ds_read_b128 v[170:173], v137 offset:32768
	ds_read_b128 v[174:177], v137 offset:33792
	ds_read_b128 v[178:181], v137 offset:34816
	ds_read_b128 v[182:185], v137 offset:35840
	ds_read_b128 v[186:189], v137 offset:36864
	ds_read_b128 v[190:193], v137 offset:37888
	ds_read_b128 v[194:197], v137 offset:38912
	ds_read_b128 v[198:201], v137 offset:39936
	s_add_i32 s57, s58, 0xb0000
	s_mov_b32 m0, s38
	s_nop 0
	buffer_load_dwordx4 v134, s[16:19], s57 offen lds
	s_nop 0
	s_mov_b32 m0, s39
	s_nop 0
	buffer_load_dwordx4 v135, s[16:19], s57 offen lds
	s_waitcnt vmcnt(8)
	s_waitcnt lgkmcnt(0)
	s_barrier
	s_setprio 1
	s_waitcnt lgkmcnt(7)
	v_mfma_f32_16x16x32_bf16 v[126:129], v[138:141], v[170:173], v[126:129]
	v_mfma_f32_16x16x32_bf16 v[122:125], v[146:149], v[170:173], v[122:125]
	s_waitcnt lgkmcnt(5)
	v_mfma_f32_16x16x32_bf16 v[118:121], v[138:141], v[178:181], v[118:121]
	v_mfma_f32_16x16x32_bf16 v[106:109], v[146:149], v[178:181], v[106:109]
	s_waitcnt lgkmcnt(3)
	v_mfma_f32_16x16x32_bf16 v[102:105], v[138:141], v[186:189], v[102:105]
	v_mfma_f32_16x16x32_bf16 v[90:93], v[146:149], v[186:189], v[90:93]
	s_waitcnt lgkmcnt(1)
	v_mfma_f32_16x16x32_bf16 v[86:89], v[138:141], v[194:197], v[86:89]
	v_mfma_f32_16x16x32_bf16 v[74:77], v[146:149], v[194:197], v[74:77]
	v_mfma_f32_16x16x32_bf16 v[126:129], v[142:145], v[174:177], v[126:129]
	v_mfma_f32_16x16x32_bf16 v[122:125], v[150:153], v[174:177], v[122:125]
	v_mfma_f32_16x16x32_bf16 v[118:121], v[142:145], v[182:185], v[118:121]
	v_mfma_f32_16x16x32_bf16 v[106:109], v[150:153], v[182:185], v[106:109]
	v_mfma_f32_16x16x32_bf16 v[102:105], v[142:145], v[190:193], v[102:105]
	v_mfma_f32_16x16x32_bf16 v[90:93], v[150:153], v[190:193], v[90:93]
	s_waitcnt lgkmcnt(0)
	v_mfma_f32_16x16x32_bf16 v[86:89], v[142:145], v[198:201], v[86:89]
	v_mfma_f32_16x16x32_bf16 v[74:77], v[150:153], v[198:201], v[74:77]
	s_setprio 0
	s_setprio 1
	v_mfma_f32_16x16x32_bf16 v[114:117], v[154:157], v[170:173], v[114:117]
	v_mfma_f32_16x16x32_bf16 v[110:113], v[162:165], v[170:173], v[110:113]
	v_mfma_f32_16x16x32_bf16 v[98:101], v[154:157], v[178:181], v[98:101]
	v_mfma_f32_16x16x32_bf16 v[94:97], v[162:165], v[178:181], v[94:97]
	v_mfma_f32_16x16x32_bf16 v[82:85], v[154:157], v[186:189], v[82:85]
	v_mfma_f32_16x16x32_bf16 v[78:81], v[162:165], v[186:189], v[78:81]
	v_mfma_f32_16x16x32_bf16 v[70:73], v[154:157], v[194:197], v[70:73]
	v_mfma_f32_16x16x32_bf16 v[66:69], v[162:165], v[194:197], v[66:69]
	v_mfma_f32_16x16x32_bf16 v[114:117], v[158:161], v[174:177], v[114:117]
	v_mfma_f32_16x16x32_bf16 v[110:113], v[166:169], v[174:177], v[110:113]
	v_mfma_f32_16x16x32_bf16 v[98:101], v[158:161], v[182:185], v[98:101]
	v_mfma_f32_16x16x32_bf16 v[94:97], v[166:169], v[182:185], v[94:97]
	v_mfma_f32_16x16x32_bf16 v[82:85], v[158:161], v[190:193], v[82:85]
	v_mfma_f32_16x16x32_bf16 v[78:81], v[166:169], v[190:193], v[78:81]
	v_mfma_f32_16x16x32_bf16 v[70:73], v[158:161], v[198:201], v[70:73]
	v_mfma_f32_16x16x32_bf16 v[66:69], v[166:169], v[198:201], v[66:69]
	s_setprio 0
	s_barrier
	ds_read_b128 v[170:173], v137 offset:49152
	ds_read_b128 v[174:177], v137 offset:50176
	s_add_i32 s57, s56, 0x80
	s_mov_b32 m0, s40
	s_nop 0
	buffer_load_dwordx4 v134, s[12:15], s57 offen lds
	ds_read_b128 v[178:181], v137 offset:51200
	ds_read_b128 v[182:185], v137 offset:52224
	s_add_i32 s56, s56, 0xb0080
	s_mov_b32 m0, s41
	s_nop 0
	buffer_load_dwordx4 v135, s[12:15], s57 offen lds
	ds_read_b128 v[186:189], v137 offset:53248
	ds_read_b128 v[190:193], v137 offset:54272
	s_nop 0
	s_mov_b32 m0, s44
	s_nop 0
	buffer_load_dwordx4 v134, s[12:15], s56 offen lds
	ds_read_b128 v[194:197], v137 offset:55296
	ds_read_b128 v[198:201], v137 offset:56320
	s_nop 0
	s_mov_b32 m0, s45
	s_nop 0
	buffer_load_dwordx4 v135, s[12:15], s56 offen lds
	s_nop 0
	s_mov_b32 m0, s42
	s_nop 0
	buffer_load_dwordx4 v134, s[16:19], s55 offen lds
	s_nop 0
	s_mov_b32 m0, s43
	s_nop 0
	buffer_load_dwordx4 v135, s[16:19], s55 offen lds
	s_waitcnt vmcnt(8)
	s_waitcnt lgkmcnt(0)
	s_barrier
	s_setprio 1
	s_waitcnt lgkmcnt(7)
	v_mfma_f32_16x16x32_bf16 v[62:65], v[138:141], v[170:173], v[62:65]
	v_mfma_f32_16x16x32_bf16 v[58:61], v[146:149], v[170:173], v[58:61]
	s_waitcnt lgkmcnt(5)
	v_mfma_f32_16x16x32_bf16 v[54:57], v[138:141], v[178:181], v[54:57]
	v_mfma_f32_16x16x32_bf16 v[42:45], v[146:149], v[178:181], v[42:45]
	s_waitcnt lgkmcnt(3)
	v_mfma_f32_16x16x32_bf16 v[38:41], v[138:141], v[186:189], v[38:41]
	v_mfma_f32_16x16x32_bf16 v[26:29], v[146:149], v[186:189], v[26:29]
	s_waitcnt lgkmcnt(1)
	v_mfma_f32_16x16x32_bf16 v[18:21], v[138:141], v[194:197], v[18:21]
	v_mfma_f32_16x16x32_bf16 v[10:13], v[146:149], v[194:197], v[10:13]
	v_mfma_f32_16x16x32_bf16 v[62:65], v[142:145], v[174:177], v[62:65]
	v_mfma_f32_16x16x32_bf16 v[58:61], v[150:153], v[174:177], v[58:61]
	v_mfma_f32_16x16x32_bf16 v[54:57], v[142:145], v[182:185], v[54:57]
	v_mfma_f32_16x16x32_bf16 v[42:45], v[150:153], v[182:185], v[42:45]
	v_mfma_f32_16x16x32_bf16 v[38:41], v[142:145], v[190:193], v[38:41]
	v_mfma_f32_16x16x32_bf16 v[26:29], v[150:153], v[190:193], v[26:29]
	s_waitcnt lgkmcnt(0)
	v_mfma_f32_16x16x32_bf16 v[18:21], v[142:145], v[198:201], v[18:21]
	v_mfma_f32_16x16x32_bf16 v[10:13], v[150:153], v[198:201], v[10:13]
	s_setprio 0
	s_setprio 1
	v_mfma_f32_16x16x32_bf16 v[50:53], v[154:157], v[170:173], v[50:53]
	v_mfma_f32_16x16x32_bf16 v[46:49], v[162:165], v[170:173], v[46:49]
	v_mfma_f32_16x16x32_bf16 v[34:37], v[154:157], v[178:181], v[34:37]
	v_mfma_f32_16x16x32_bf16 v[30:33], v[162:165], v[178:181], v[30:33]
	v_mfma_f32_16x16x32_bf16 v[22:25], v[154:157], v[186:189], v[22:25]
	v_mfma_f32_16x16x32_bf16 v[14:17], v[162:165], v[186:189], v[14:17]
	v_mfma_f32_16x16x32_bf16 v[6:9], v[154:157], v[194:197], v[6:9]
	v_mfma_f32_16x16x32_bf16 v[2:5], v[162:165], v[194:197], v[2:5]
	v_mfma_f32_16x16x32_bf16 v[50:53], v[158:161], v[174:177], v[50:53]
	v_mfma_f32_16x16x32_bf16 v[46:49], v[166:169], v[174:177], v[46:49]
	v_mfma_f32_16x16x32_bf16 v[34:37], v[158:161], v[182:185], v[34:37]
	v_mfma_f32_16x16x32_bf16 v[30:33], v[166:169], v[182:185], v[30:33]
	v_mfma_f32_16x16x32_bf16 v[22:25], v[158:161], v[190:193], v[22:25]
	v_mfma_f32_16x16x32_bf16 v[14:17], v[166:169], v[190:193], v[14:17]
	v_mfma_f32_16x16x32_bf16 v[6:9], v[158:161], v[198:201], v[6:9]
	v_mfma_f32_16x16x32_bf16 v[2:5], v[166:169], v[198:201], v[2:5]
	s_setprio 0
	s_barrier
	s_add_i32 s2, s2, 2
	s_addk_i32 s3, 0x100
	s_cmp_gt_u32 s2, 41
	s_cbranch_scc0 .LBB0_1135
	s_andn2_b64 vcc, exec, s[4:5]
	s_cbranch_vccnz .LBB0_1123
	v_mov_b32_e32 v2, 0
	s_mov_b32 s20, s50
	s_mov_b32 s25, s51
	s_mov_b32 s30, s54
	s_mov_b32 s36, s53
	s_mov_b32 s49, s52
	v_mov_b32_e32 v3, v2
	v_mov_b32_e32 v4, v2
	v_mov_b32_e32 v5, v2
	v_mov_b32_e32 v6, v2
	v_mov_b32_e32 v7, v2
	v_mov_b32_e32 v8, v2
	v_mov_b32_e32 v9, v2
	v_mov_b32_e32 v14, v2
	v_mov_b32_e32 v15, v2
	v_mov_b32_e32 v16, v2
	v_mov_b32_e32 v17, v2
	v_mov_b32_e32 v22, v2
	v_mov_b32_e32 v23, v2
	v_mov_b32_e32 v24, v2
	v_mov_b32_e32 v25, v2
	v_mov_b32_e32 v30, v2
	v_mov_b32_e32 v31, v2
	v_mov_b32_e32 v32, v2
	v_mov_b32_e32 v33, v2
	v_mov_b32_e32 v34, v2
	v_mov_b32_e32 v35, v2
	v_mov_b32_e32 v36, v2
	v_mov_b32_e32 v37, v2
	v_mov_b32_e32 v46, v2
	v_mov_b32_e32 v47, v2
	v_mov_b32_e32 v48, v2
	v_mov_b32_e32 v49, v2
	v_mov_b32_e32 v50, v2
	v_mov_b32_e32 v51, v2
	v_mov_b32_e32 v52, v2
	v_mov_b32_e32 v53, v2
	v_mov_b32_e32 v10, v2
	v_mov_b32_e32 v11, v2
	v_mov_b32_e32 v12, v2
	v_mov_b32_e32 v13, v2
	v_mov_b32_e32 v18, v2
	v_mov_b32_e32 v19, v2
	v_mov_b32_e32 v20, v2
	v_mov_b32_e32 v21, v2
	v_mov_b32_e32 v26, v2
	v_mov_b32_e32 v27, v2
	v_mov_b32_e32 v28, v2
	v_mov_b32_e32 v29, v2
	v_mov_b32_e32 v38, v2
	v_mov_b32_e32 v39, v2
	v_mov_b32_e32 v40, v2
	v_mov_b32_e32 v41, v2
	v_mov_b32_e32 v42, v2
	v_mov_b32_e32 v43, v2
	v_mov_b32_e32 v44, v2
	v_mov_b32_e32 v45, v2
	v_mov_b32_e32 v54, v2
	v_mov_b32_e32 v55, v2
	v_mov_b32_e32 v56, v2
	v_mov_b32_e32 v57, v2
	v_mov_b32_e32 v58, v2
	v_mov_b32_e32 v59, v2
	v_mov_b32_e32 v60, v2
	v_mov_b32_e32 v61, v2
	v_mov_b32_e32 v62, v2
	v_mov_b32_e32 v63, v2
	v_mov_b32_e32 v64, v2
	v_mov_b32_e32 v65, v2
	v_mov_b32_e32 v66, v2
	v_mov_b32_e32 v67, v2
	v_mov_b32_e32 v68, v2
	v_mov_b32_e32 v69, v2
	v_mov_b32_e32 v70, v2
	v_mov_b32_e32 v71, v2
	v_mov_b32_e32 v72, v2
	v_mov_b32_e32 v73, v2
	v_mov_b32_e32 v78, v2
	v_mov_b32_e32 v79, v2
	v_mov_b32_e32 v80, v2
	v_mov_b32_e32 v81, v2
	v_mov_b32_e32 v82, v2
	v_mov_b32_e32 v83, v2
	v_mov_b32_e32 v84, v2
	v_mov_b32_e32 v85, v2
	v_mov_b32_e32 v94, v2
	v_mov_b32_e32 v95, v2
	v_mov_b32_e32 v96, v2
	v_mov_b32_e32 v97, v2
	v_mov_b32_e32 v98, v2
	v_mov_b32_e32 v99, v2
	v_mov_b32_e32 v100, v2
	v_mov_b32_e32 v101, v2
	v_mov_b32_e32 v110, v2
	v_mov_b32_e32 v111, v2
	v_mov_b32_e32 v112, v2
	v_mov_b32_e32 v113, v2
	v_mov_b32_e32 v114, v2
	v_mov_b32_e32 v115, v2
	v_mov_b32_e32 v116, v2
	v_mov_b32_e32 v117, v2
	v_mov_b32_e32 v74, v2
	v_mov_b32_e32 v75, v2
	v_mov_b32_e32 v76, v2
	v_mov_b32_e32 v77, v2
	v_mov_b32_e32 v86, v2
	v_mov_b32_e32 v87, v2
	v_mov_b32_e32 v88, v2
	v_mov_b32_e32 v89, v2
	v_mov_b32_e32 v90, v2
	v_mov_b32_e32 v91, v2
	v_mov_b32_e32 v92, v2
	v_mov_b32_e32 v93, v2
	v_mov_b32_e32 v102, v2
	v_mov_b32_e32 v103, v2
	v_mov_b32_e32 v104, v2
	v_mov_b32_e32 v105, v2
	v_mov_b32_e32 v106, v2
	v_mov_b32_e32 v107, v2
	v_mov_b32_e32 v108, v2
	v_mov_b32_e32 v109, v2
	v_mov_b32_e32 v118, v2
	v_mov_b32_e32 v119, v2
	v_mov_b32_e32 v120, v2
	v_mov_b32_e32 v121, v2
	v_mov_b32_e32 v122, v2
	v_mov_b32_e32 v123, v2
	v_mov_b32_e32 v124, v2
	v_mov_b32_e32 v125, v2
	v_mov_b32_e32 v126, v2
	v_mov_b32_e32 v127, v2
	v_mov_b32_e32 v128, v2
	v_mov_b32_e32 v129, v2
	s_branch .LBB0_1123
